# RWKV scan: state kept divided by the cumulative decay of its 16-step group (helpers pre-scale k,kd,b,r tables with prefix-summed log-decay; group decay applied at the boundary): 4 fewer VALU + 1 fewer
# speedup vs baseline: 1.0307x; 1.0236x over previous
; template <int CTRL> __device__ __forceinline__ float dppf(float x) { return __builtin_bit_cast(float, __builtin_amdgcn_update_dpp(0, __builtin_bit_cast(int, x), CTRL, 0xF, 0xF, false)); }
; __device__ __forceinline__ void phase_rwkv_scan(const Fr& F, int jr) {
;     ...
;                 for (int pg = 0; pg < 64; pg += 16) {
; #pragma unroll
;                     for (int pi = 0; pi < 16; ++pi) {
;                         const int p = pg + pi, pn = p < 63 ? p + 1 : 63;
;                         const f32x4 w4n = PW[pn * 16], k4n = PW[1024 + pn * 16], b4n = PW[2048 + pn * 16], d4n = PW[3072 + pn * 16], r4n = PR[pn * 16];
;                         const float vvn = PV[pn * 32];
;                         f32x2 t = S01 * k4.xy; t = S23 * k4.zw + t; float sa = t.x + t.y;
;                         sa += dppf<0x128>(sa);
;                         const f32x2 dv01 = d4.xy * vv, dv23 = d4.zw * vv;
;                         sa += dppf<0x124>(sa);
;                         const f32x2 e01 = S01 * w4.xy + dv01;
;                         sa += dppf<0x122>(sa);
;                         const f32x2 e23 = S23 * w4.zw + dv23;
;                         sa += dppf<0x121>(sa);
;                         S01 = e01 - b4.xy * sa; S23 = e23 - b4.zw * sa;
;                         f32x2 u = S01 * r4.xy; u = S23 * r4.zw + u;
;                         PY[pi * 64] = u.x + u.y;
;                         w4 = w4n; k4 = k4n; b4 = b4n; d4 = d4n; r4 = r4n; vv = vvn;
;                     }
.Lrw0_shc:
	v_add_u32_e32 v240, s11, v214
	v_add_u32_e32 v242, s11, v216
	ds_read_b128 v[84:87], v240 offset:8704
	ds_read_b128 v[56:59], v242 offset:43520
	ds_read_b128 v[92:95], v240 offset:26112
	ds_read_b128 v[88:91], v240 offset:17408
	ds_read_b128 v[96:99], v240 offset:34816
	ds_read_b128 v[106:109], v240 offset:8976
	ds_read_b128 v[114:117], v240 offset:26384
	ds_read_b128 v[110:113], v240 offset:17680
	s_waitcnt lgkmcnt(4)
	v_pk_mul_f32 v[226:227], v[206:207], v[84:85] op_sel_hi:[1,0]
	v_pk_fma_f32 v[232:233], v[56:57], v[92:93], v[206:207] op_sel_hi:[1,0,1]
	v_pk_fma_f32 v[226:227], v[208:209], v[84:85], v[226:227] op_sel:[0,1,0]
	v_pk_fma_f32 v[234:235], v[56:57], v[92:93], v[208:209] op_sel:[0,1,0]
	v_pk_fma_f32 v[226:227], v[210:211], v[86:87], v[226:227] op_sel_hi:[1,0,1]
	v_pk_fma_f32 v[236:237], v[56:57], v[94:95], v[210:211] op_sel_hi:[1,0,1]
	v_pk_fma_f32 v[226:227], v[212:213], v[86:87], v[226:227] op_sel:[0,1,0]
	v_pk_fma_f32 v[238:239], v[56:57], v[94:95], v[212:213] op_sel:[0,1,0]
	ds_read_b128 v[12:15], v240 offset:26656
	v_add_f32_dpp v230, v227, v226 row_ror:8 row_mask:0xf bank_mask:0xf
	ds_read_b128 v[8:11], v240 offset:17952
	ds_read_b128 v[4:7], v240 offset:9248
	v_add_f32_dpp v230, v230, v230 quad_perm:[1,0,3,2] row_mask:0xf bank_mask:0xf
	ds_read_b128 v[222:225], v240 offset:35088
	ds_read_b128 v[60:63], v242 offset:44048
	v_add_f32_dpp v230, v230, v230 quad_perm:[2,3,0,1] row_mask:0xf bank_mask:0xf
	s_nop 1
	v_add_f32_dpp v230, v230, v230 row_half_mirror row_mask:0xf bank_mask:0xf
	s_nop 1
	v_mov_b32_dpp v231, v230 row_ror:8 row_mask:0xf bank_mask:0xf
	v_pk_fma_f32 v[206:207], v[88:89], v[230:231], v[232:233] op_sel_hi:[0,1,1] neg_lo:[1,0,0] neg_hi:[1,0,0]
	v_pk_fma_f32 v[208:209], v[88:89], v[230:231], v[234:235] op_sel:[1,0,0] neg_lo:[1,0,0] neg_hi:[1,0,0]
	v_pk_fma_f32 v[210:211], v[90:91], v[230:231], v[236:237] op_sel_hi:[0,1,1] neg_lo:[1,0,0] neg_hi:[1,0,0]
	v_pk_fma_f32 v[212:213], v[90:91], v[230:231], v[238:239] op_sel:[1,0,0] neg_lo:[1,0,0] neg_hi:[1,0,0]
	s_waitcnt lgkmcnt(5)
	v_pk_mul_f32 v[226:227], v[206:207], v[106:107] op_sel_hi:[1,0]
	v_pk_mul_f32 v[228:229], v[206:207], v[96:97] op_sel_hi:[1,0]
	v_pk_fma_f32 v[226:227], v[208:209], v[106:107], v[226:227] op_sel:[0,1,0]
	v_pk_fma_f32 v[228:229], v[208:209], v[96:97], v[228:229] op_sel:[0,1,0]
	v_pk_fma_f32 v[226:227], v[210:211], v[108:109], v[226:227] op_sel_hi:[1,0,1]
	v_pk_fma_f32 v[228:229], v[210:211], v[98:99], v[228:229] op_sel_hi:[1,0,1]
	v_pk_fma_f32 v[226:227], v[212:213], v[108:109], v[226:227] op_sel:[0,1,0]
	v_pk_fma_f32 v[228:229], v[212:213], v[98:99], v[228:229] op_sel:[0,1,0]
	v_pk_fma_f32 v[232:233], v[58:59], v[114:115], v[206:207] op_sel_hi:[1,0,1]
	v_add_f32_dpp v230, v227, v226 row_ror:8 row_mask:0xf bank_mask:0xf
	v_pk_fma_f32 v[234:235], v[58:59], v[114:115], v[208:209] op_sel:[0,1,0]
	v_pk_fma_f32 v[236:237], v[58:59], v[116:117], v[210:211] op_sel_hi:[1,0,1]
	v_add_f32_dpp v230, v230, v230 quad_perm:[1,0,3,2] row_mask:0xf bank_mask:0xf
	v_pk_fma_f32 v[238:239], v[58:59], v[116:117], v[212:213] op_sel:[0,1,0]
	ds_read_b128 v[96:99], v240 offset:35360
	v_add_f32_dpp v230, v230, v230 quad_perm:[2,3,0,1] row_mask:0xf bank_mask:0xf
	ds_read_b128 v[92:95], v240 offset:26928
	ds_read_b128 v[88:91], v240 offset:18224
	v_add_f32_dpp v230, v230, v230 row_half_mirror row_mask:0xf bank_mask:0xf
	ds_write_b64 v217, v[228:229] offset:0
	ds_read_b128 v[84:87], v240 offset:9520
	v_mov_b32_dpp v231, v230 row_ror:8 row_mask:0xf bank_mask:0xf
	v_pk_fma_f32 v[206:207], v[110:111], v[230:231], v[232:233] op_sel_hi:[0,1,1] neg_lo:[1,0,0] neg_hi:[1,0,0]
	v_pk_fma_f32 v[208:209], v[110:111], v[230:231], v[234:235] op_sel:[1,0,0] neg_lo:[1,0,0] neg_hi:[1,0,0]
	v_pk_fma_f32 v[210:211], v[112:113], v[230:231], v[236:237] op_sel_hi:[0,1,1] neg_lo:[1,0,0] neg_hi:[1,0,0]
	v_pk_fma_f32 v[212:213], v[112:113], v[230:231], v[238:239] op_sel:[1,0,0] neg_lo:[1,0,0] neg_hi:[1,0,0]
	s_waitcnt lgkmcnt(5)
	ds_read_b128 v[56:59], v242 offset:44576
	v_pk_mul_f32 v[226:227], v[206:207], v[4:5] op_sel_hi:[1,0]
	v_pk_mul_f32 v[228:229], v[206:207], v[222:223] op_sel_hi:[1,0]
	v_pk_fma_f32 v[226:227], v[208:209], v[4:5], v[226:227] op_sel:[0,1,0]
	v_pk_fma_f32 v[228:229], v[208:209], v[222:223], v[228:229] op_sel:[0,1,0]
	v_pk_fma_f32 v[226:227], v[210:211], v[6:7], v[226:227] op_sel_hi:[1,0,1]
	v_pk_fma_f32 v[228:229], v[210:211], v[224:225], v[228:229] op_sel_hi:[1,0,1]
	v_pk_fma_f32 v[226:227], v[212:213], v[6:7], v[226:227] op_sel:[0,1,0]
	v_pk_fma_f32 v[228:229], v[212:213], v[224:225], v[228:229] op_sel:[0,1,0]
	v_pk_fma_f32 v[232:233], v[60:61], v[12:13], v[206:207] op_sel_hi:[1,0,1]
	v_add_f32_dpp v230, v227, v226 row_ror:8 row_mask:0xf bank_mask:0xf
	v_pk_fma_f32 v[234:235], v[60:61], v[12:13], v[208:209] op_sel:[0,1,0]
	v_pk_fma_f32 v[236:237], v[60:61], v[14:15], v[210:211] op_sel_hi:[1,0,1]
	v_add_f32_dpp v230, v230, v230 quad_perm:[1,0,3,2] row_mask:0xf bank_mask:0xf
	v_pk_fma_f32 v[238:239], v[60:61], v[14:15], v[212:213] op_sel:[0,1,0]
	ds_read_b128 v[222:225], v240 offset:35632
	v_add_f32_dpp v230, v230, v230 quad_perm:[2,3,0,1] row_mask:0xf bank_mask:0xf
	ds_read_b128 v[114:117], v240 offset:27200
	ds_read_b128 v[110:113], v240 offset:18496
	v_add_f32_dpp v230, v230, v230 row_half_mirror row_mask:0xf bank_mask:0xf
	ds_write_b64 v217, v[228:229] offset:576
	ds_read_b128 v[106:109], v240 offset:9792
	v_mov_b32_dpp v231, v230 row_ror:8 row_mask:0xf bank_mask:0xf
	v_pk_fma_f32 v[206:207], v[8:9], v[230:231], v[232:233] op_sel_hi:[0,1,1] neg_lo:[1,0,0] neg_hi:[1,0,0]
	v_pk_fma_f32 v[208:209], v[8:9], v[230:231], v[234:235] op_sel:[1,0,0] neg_lo:[1,0,0] neg_hi:[1,0,0]
	v_pk_fma_f32 v[210:211], v[10:11], v[230:231], v[236:237] op_sel_hi:[0,1,1] neg_lo:[1,0,0] neg_hi:[1,0,0]
	v_pk_fma_f32 v[212:213], v[10:11], v[230:231], v[238:239] op_sel:[1,0,0] neg_lo:[1,0,0] neg_hi:[1,0,0]
	s_waitcnt lgkmcnt(6)
; template <int CTRL> __device__ __forceinline__ float dppf(float x) { return __builtin_bit_cast(float, __builtin_amdgcn_update_dpp(0, __builtin_bit_cast(int, x), CTRL, 0xF, 0xF, false)); }
; __device__ __forceinline__ void phase_rwkv_scan(const Fr& F, int jr) {
;     ...
;                 for (int pg = 0; pg < 64; pg += 16) {
; #pragma unroll
;                     for (int pi = 0; pi < 16; ++pi) {
;                         const int p = pg + pi, pn = p < 63 ? p + 1 : 63;
;                         const f32x4 w4n = PW[pn * 16], k4n = PW[1024 + pn * 16], b4n = PW[2048 + pn * 16], d4n = PW[3072 + pn * 16], r4n = PR[pn * 16];
;                         const float vvn = PV[pn * 32];
;                         f32x2 t = S01 * k4.xy; t = S23 * k4.zw + t; float sa = t.x + t.y;
;                         sa += dppf<0x128>(sa);
;                         const f32x2 dv01 = d4.xy * vv, dv23 = d4.zw * vv;
;                         sa += dppf<0x124>(sa);
;                         const f32x2 e01 = S01 * w4.xy + dv01;
;                         sa += dppf<0x122>(sa);
;                         const f32x2 e23 = S23 * w4.zw + dv23;
;                         sa += dppf<0x121>(sa);
;                         S01 = e01 - b4.xy * sa; S23 = e23 - b4.zw * sa;
;                         f32x2 u = S01 * r4.xy; u = S23 * r4.zw + u;
;                         PY[pi * 64] = u.x + u.y;
;                         w4 = w4n; k4 = k4n; b4 = b4n; d4 = d4n; r4 = r4n; vv = vvn;
;                     }
	v_pk_mul_f32 v[226:227], v[206:207], v[84:85] op_sel_hi:[1,0]
	v_pk_mul_f32 v[228:229], v[206:207], v[96:97] op_sel_hi:[1,0]
	v_pk_fma_f32 v[226:227], v[208:209], v[84:85], v[226:227] op_sel:[0,1,0]
	v_pk_fma_f32 v[228:229], v[208:209], v[96:97], v[228:229] op_sel:[0,1,0]
	v_pk_fma_f32 v[226:227], v[210:211], v[86:87], v[226:227] op_sel_hi:[1,0,1]
	v_pk_fma_f32 v[228:229], v[210:211], v[98:99], v[228:229] op_sel_hi:[1,0,1]
	v_pk_fma_f32 v[226:227], v[212:213], v[86:87], v[226:227] op_sel:[0,1,0]
	v_pk_fma_f32 v[228:229], v[212:213], v[98:99], v[228:229] op_sel:[0,1,0]
	v_pk_fma_f32 v[232:233], v[62:63], v[92:93], v[206:207] op_sel_hi:[1,0,1]
	v_add_f32_dpp v230, v227, v226 row_ror:8 row_mask:0xf bank_mask:0xf
	v_pk_fma_f32 v[234:235], v[62:63], v[92:93], v[208:209] op_sel:[0,1,0]
	v_pk_fma_f32 v[236:237], v[62:63], v[94:95], v[210:211] op_sel_hi:[1,0,1]
	v_add_f32_dpp v230, v230, v230 quad_perm:[1,0,3,2] row_mask:0xf bank_mask:0xf
	v_pk_fma_f32 v[238:239], v[62:63], v[94:95], v[212:213] op_sel:[0,1,0]
	ds_read_b128 v[96:99], v240 offset:35904
	v_add_f32_dpp v230, v230, v230 quad_perm:[2,3,0,1] row_mask:0xf bank_mask:0xf
	ds_read_b128 v[12:15], v240 offset:27472
	ds_read_b128 v[8:11], v240 offset:18768
	v_add_f32_dpp v230, v230, v230 row_half_mirror row_mask:0xf bank_mask:0xf
	ds_write_b64 v217, v[228:229] offset:1152
	ds_read_b128 v[4:7], v240 offset:10064
	v_mov_b32_dpp v231, v230 row_ror:8 row_mask:0xf bank_mask:0xf
	v_pk_fma_f32 v[206:207], v[88:89], v[230:231], v[232:233] op_sel_hi:[0,1,1] neg_lo:[1,0,0] neg_hi:[1,0,0]
	v_pk_fma_f32 v[208:209], v[88:89], v[230:231], v[234:235] op_sel:[1,0,0] neg_lo:[1,0,0] neg_hi:[1,0,0]
	v_pk_fma_f32 v[210:211], v[90:91], v[230:231], v[236:237] op_sel_hi:[0,1,1] neg_lo:[1,0,0] neg_hi:[1,0,0]
	v_pk_fma_f32 v[212:213], v[90:91], v[230:231], v[238:239] op_sel:[1,0,0] neg_lo:[1,0,0] neg_hi:[1,0,0]
	s_waitcnt lgkmcnt(5)
	ds_read_b128 v[60:63], v242 offset:45104
	v_pk_mul_f32 v[226:227], v[206:207], v[106:107] op_sel_hi:[1,0]
	v_pk_mul_f32 v[228:229], v[206:207], v[222:223] op_sel_hi:[1,0]
	v_pk_fma_f32 v[226:227], v[208:209], v[106:107], v[226:227] op_sel:[0,1,0]
	v_pk_fma_f32 v[228:229], v[208:209], v[222:223], v[228:229] op_sel:[0,1,0]
	v_pk_fma_f32 v[226:227], v[210:211], v[108:109], v[226:227] op_sel_hi:[1,0,1]
	v_pk_fma_f32 v[228:229], v[210:211], v[224:225], v[228:229] op_sel_hi:[1,0,1]
	v_pk_fma_f32 v[226:227], v[212:213], v[108:109], v[226:227] op_sel:[0,1,0]
	v_pk_fma_f32 v[228:229], v[212:213], v[224:225], v[228:229] op_sel:[0,1,0]
	v_pk_fma_f32 v[232:233], v[56:57], v[114:115], v[206:207] op_sel_hi:[1,0,1]
	v_add_f32_dpp v230, v227, v226 row_ror:8 row_mask:0xf bank_mask:0xf
	v_pk_fma_f32 v[234:235], v[56:57], v[114:115], v[208:209] op_sel:[0,1,0]
	v_pk_fma_f32 v[236:237], v[56:57], v[116:117], v[210:211] op_sel_hi:[1,0,1]
	v_add_f32_dpp v230, v230, v230 quad_perm:[1,0,3,2] row_mask:0xf bank_mask:0xf
	v_pk_fma_f32 v[238:239], v[56:57], v[116:117], v[212:213] op_sel:[0,1,0]
	ds_read_b128 v[222:225], v240 offset:36176
	v_add_f32_dpp v230, v230, v230 quad_perm:[2,3,0,1] row_mask:0xf bank_mask:0xf
	ds_read_b128 v[92:95], v240 offset:27744
	ds_read_b128 v[88:91], v240 offset:19040
	v_add_f32_dpp v230, v230, v230 row_half_mirror row_mask:0xf bank_mask:0xf
	ds_write_b64 v217, v[228:229] offset:1728
	ds_read_b128 v[84:87], v240 offset:10336
	v_mov_b32_dpp v231, v230 row_ror:8 row_mask:0xf bank_mask:0xf
	v_pk_fma_f32 v[206:207], v[110:111], v[230:231], v[232:233] op_sel_hi:[0,1,1] neg_lo:[1,0,0] neg_hi:[1,0,0]
	v_pk_fma_f32 v[208:209], v[110:111], v[230:231], v[234:235] op_sel:[1,0,0] neg_lo:[1,0,0] neg_hi:[1,0,0]
	v_pk_fma_f32 v[210:211], v[112:113], v[230:231], v[236:237] op_sel_hi:[0,1,1] neg_lo:[1,0,0] neg_hi:[1,0,0]
	v_pk_fma_f32 v[212:213], v[112:113], v[230:231], v[238:239] op_sel:[1,0,0] neg_lo:[1,0,0] neg_hi:[1,0,0]
	s_waitcnt lgkmcnt(6)
	v_pk_mul_f32 v[226:227], v[206:207], v[4:5] op_sel_hi:[1,0]
	v_pk_mul_f32 v[228:229], v[206:207], v[96:97] op_sel_hi:[1,0]
	v_pk_fma_f32 v[226:227], v[208:209], v[4:5], v[226:227] op_sel:[0,1,0]
	v_pk_fma_f32 v[228:229], v[208:209], v[96:97], v[228:229] op_sel:[0,1,0]
	v_pk_fma_f32 v[226:227], v[210:211], v[6:7], v[226:227] op_sel_hi:[1,0,1]
	v_pk_fma_f32 v[228:229], v[210:211], v[98:99], v[228:229] op_sel_hi:[1,0,1]
	v_pk_fma_f32 v[226:227], v[212:213], v[6:7], v[226:227] op_sel:[0,1,0]
	v_pk_fma_f32 v[228:229], v[212:213], v[98:99], v[228:229] op_sel:[0,1,0]
	v_pk_fma_f32 v[232:233], v[58:59], v[12:13], v[206:207] op_sel_hi:[1,0,1]
	v_add_f32_dpp v230, v227, v226 row_ror:8 row_mask:0xf bank_mask:0xf
	v_pk_fma_f32 v[234:235], v[58:59], v[12:13], v[208:209] op_sel:[0,1,0]
	v_pk_fma_f32 v[236:237], v[58:59], v[14:15], v[210:211] op_sel_hi:[1,0,1]
	v_add_f32_dpp v230, v230, v230 quad_perm:[1,0,3,2] row_mask:0xf bank_mask:0xf
	v_pk_fma_f32 v[238:239], v[58:59], v[14:15], v[212:213] op_sel:[0,1,0]
	ds_read_b128 v[96:99], v240 offset:36448
	v_add_f32_dpp v230, v230, v230 quad_perm:[2,3,0,1] row_mask:0xf bank_mask:0xf
	ds_read_b128 v[114:117], v240 offset:28016
	ds_read_b128 v[110:113], v240 offset:19312
	v_add_f32_dpp v230, v230, v230 row_half_mirror row_mask:0xf bank_mask:0xf
	ds_write_b64 v217, v[228:229] offset:2304
	ds_read_b128 v[106:109], v240 offset:10608
	v_mov_b32_dpp v231, v230 row_ror:8 row_mask:0xf bank_mask:0xf
	v_pk_fma_f32 v[206:207], v[8:9], v[230:231], v[232:233] op_sel_hi:[0,1,1] neg_lo:[1,0,0] neg_hi:[1,0,0]
	v_pk_fma_f32 v[208:209], v[8:9], v[230:231], v[234:235] op_sel:[1,0,0] neg_lo:[1,0,0] neg_hi:[1,0,0]
	v_pk_fma_f32 v[210:211], v[10:11], v[230:231], v[236:237] op_sel_hi:[0,1,1] neg_lo:[1,0,0] neg_hi:[1,0,0]
	v_pk_fma_f32 v[212:213], v[10:11], v[230:231], v[238:239] op_sel:[1,0,0] neg_lo:[1,0,0] neg_hi:[1,0,0]
	s_waitcnt lgkmcnt(5)
; template <int CTRL> __device__ __forceinline__ float dppf(float x) { return __builtin_bit_cast(float, __builtin_amdgcn_update_dpp(0, __builtin_bit_cast(int, x), CTRL, 0xF, 0xF, false)); }
; __device__ __forceinline__ void phase_rwkv_scan(const Fr& F, int jr) {
;     ...
;                 for (int pg = 0; pg < 64; pg += 16) {
; #pragma unroll
;                     for (int pi = 0; pi < 16; ++pi) {
;                         const int p = pg + pi, pn = p < 63 ? p + 1 : 63;
;                         const f32x4 w4n = PW[pn * 16], k4n = PW[1024 + pn * 16], b4n = PW[2048 + pn * 16], d4n = PW[3072 + pn * 16], r4n = PR[pn * 16];
;                         const float vvn = PV[pn * 32];
;                         f32x2 t = S01 * k4.xy; t = S23 * k4.zw + t; float sa = t.x + t.y;
;                         sa += dppf<0x128>(sa);
;                         const f32x2 dv01 = d4.xy * vv, dv23 = d4.zw * vv;
;                         sa += dppf<0x124>(sa);
;                         const f32x2 e01 = S01 * w4.xy + dv01;
;                         sa += dppf<0x122>(sa);
;                         const f32x2 e23 = S23 * w4.zw + dv23;
;                         sa += dppf<0x121>(sa);
;                         S01 = e01 - b4.xy * sa; S23 = e23 - b4.zw * sa;
;                         f32x2 u = S01 * r4.xy; u = S23 * r4.zw + u;
;                         PY[pi * 64] = u.x + u.y;
;                         w4 = w4n; k4 = k4n; b4 = b4n; d4 = d4n; r4 = r4n; vv = vvn;
;                     }
	ds_read_b128 v[56:59], v242 offset:45632
	v_pk_mul_f32 v[226:227], v[206:207], v[84:85] op_sel_hi:[1,0]
	v_pk_mul_f32 v[228:229], v[206:207], v[222:223] op_sel_hi:[1,0]
	v_pk_fma_f32 v[226:227], v[208:209], v[84:85], v[226:227] op_sel:[0,1,0]
	v_pk_fma_f32 v[228:229], v[208:209], v[222:223], v[228:229] op_sel:[0,1,0]
	v_pk_fma_f32 v[226:227], v[210:211], v[86:87], v[226:227] op_sel_hi:[1,0,1]
	v_pk_fma_f32 v[228:229], v[210:211], v[224:225], v[228:229] op_sel_hi:[1,0,1]
	v_pk_fma_f32 v[226:227], v[212:213], v[86:87], v[226:227] op_sel:[0,1,0]
	v_pk_fma_f32 v[228:229], v[212:213], v[224:225], v[228:229] op_sel:[0,1,0]
	v_pk_fma_f32 v[232:233], v[60:61], v[92:93], v[206:207] op_sel_hi:[1,0,1]
	v_add_f32_dpp v230, v227, v226 row_ror:8 row_mask:0xf bank_mask:0xf
	v_pk_fma_f32 v[234:235], v[60:61], v[92:93], v[208:209] op_sel:[0,1,0]
	v_pk_fma_f32 v[236:237], v[60:61], v[94:95], v[210:211] op_sel_hi:[1,0,1]
	v_add_f32_dpp v230, v230, v230 quad_perm:[1,0,3,2] row_mask:0xf bank_mask:0xf
	v_pk_fma_f32 v[238:239], v[60:61], v[94:95], v[212:213] op_sel:[0,1,0]
	ds_read_b128 v[222:225], v240 offset:36720
	v_add_f32_dpp v230, v230, v230 quad_perm:[2,3,0,1] row_mask:0xf bank_mask:0xf
	ds_read_b128 v[12:15], v240 offset:28288
	ds_read_b128 v[8:11], v240 offset:19584
	v_add_f32_dpp v230, v230, v230 row_half_mirror row_mask:0xf bank_mask:0xf
	ds_write_b64 v217, v[228:229] offset:2880
	ds_read_b128 v[4:7], v240 offset:10880
	v_mov_b32_dpp v231, v230 row_ror:8 row_mask:0xf bank_mask:0xf
	v_pk_fma_f32 v[206:207], v[88:89], v[230:231], v[232:233] op_sel_hi:[0,1,1] neg_lo:[1,0,0] neg_hi:[1,0,0]
	v_pk_fma_f32 v[208:209], v[88:89], v[230:231], v[234:235] op_sel:[1,0,0] neg_lo:[1,0,0] neg_hi:[1,0,0]
	v_pk_fma_f32 v[210:211], v[90:91], v[230:231], v[236:237] op_sel_hi:[0,1,1] neg_lo:[1,0,0] neg_hi:[1,0,0]
	v_pk_fma_f32 v[212:213], v[90:91], v[230:231], v[238:239] op_sel:[1,0,0] neg_lo:[1,0,0] neg_hi:[1,0,0]
	s_waitcnt lgkmcnt(6)
	v_pk_mul_f32 v[226:227], v[206:207], v[106:107] op_sel_hi:[1,0]
	v_pk_mul_f32 v[228:229], v[206:207], v[96:97] op_sel_hi:[1,0]
	v_pk_fma_f32 v[226:227], v[208:209], v[106:107], v[226:227] op_sel:[0,1,0]
	v_pk_fma_f32 v[228:229], v[208:209], v[96:97], v[228:229] op_sel:[0,1,0]
	v_pk_fma_f32 v[226:227], v[210:211], v[108:109], v[226:227] op_sel_hi:[1,0,1]
	v_pk_fma_f32 v[228:229], v[210:211], v[98:99], v[228:229] op_sel_hi:[1,0,1]
	v_pk_fma_f32 v[226:227], v[212:213], v[108:109], v[226:227] op_sel:[0,1,0]
	v_pk_fma_f32 v[228:229], v[212:213], v[98:99], v[228:229] op_sel:[0,1,0]
	v_pk_fma_f32 v[232:233], v[62:63], v[114:115], v[206:207] op_sel_hi:[1,0,1]
	v_add_f32_dpp v230, v227, v226 row_ror:8 row_mask:0xf bank_mask:0xf
	v_pk_fma_f32 v[234:235], v[62:63], v[114:115], v[208:209] op_sel:[0,1,0]
	v_pk_fma_f32 v[236:237], v[62:63], v[116:117], v[210:211] op_sel_hi:[1,0,1]
	v_add_f32_dpp v230, v230, v230 quad_perm:[1,0,3,2] row_mask:0xf bank_mask:0xf
	v_pk_fma_f32 v[238:239], v[62:63], v[116:117], v[212:213] op_sel:[0,1,0]
	ds_read_b128 v[96:99], v240 offset:36992
	v_add_f32_dpp v230, v230, v230 quad_perm:[2,3,0,1] row_mask:0xf bank_mask:0xf
	ds_read_b128 v[92:95], v240 offset:28560
	ds_read_b128 v[88:91], v240 offset:19856
	v_add_f32_dpp v230, v230, v230 row_half_mirror row_mask:0xf bank_mask:0xf
	ds_write_b64 v217, v[228:229] offset:3456
	ds_read_b128 v[84:87], v240 offset:11152
	v_mov_b32_dpp v231, v230 row_ror:8 row_mask:0xf bank_mask:0xf
	v_pk_fma_f32 v[206:207], v[110:111], v[230:231], v[232:233] op_sel_hi:[0,1,1] neg_lo:[1,0,0] neg_hi:[1,0,0]
	v_pk_fma_f32 v[208:209], v[110:111], v[230:231], v[234:235] op_sel:[1,0,0] neg_lo:[1,0,0] neg_hi:[1,0,0]
	v_pk_fma_f32 v[210:211], v[112:113], v[230:231], v[236:237] op_sel_hi:[0,1,1] neg_lo:[1,0,0] neg_hi:[1,0,0]
	v_pk_fma_f32 v[212:213], v[112:113], v[230:231], v[238:239] op_sel:[1,0,0] neg_lo:[1,0,0] neg_hi:[1,0,0]
	s_waitcnt lgkmcnt(5)
	ds_read_b128 v[60:63], v242 offset:46160
	v_pk_mul_f32 v[226:227], v[206:207], v[4:5] op_sel_hi:[1,0]
	v_pk_mul_f32 v[228:229], v[206:207], v[222:223] op_sel_hi:[1,0]
	v_pk_fma_f32 v[226:227], v[208:209], v[4:5], v[226:227] op_sel:[0,1,0]
	v_pk_fma_f32 v[228:229], v[208:209], v[222:223], v[228:229] op_sel:[0,1,0]
	v_pk_fma_f32 v[226:227], v[210:211], v[6:7], v[226:227] op_sel_hi:[1,0,1]
	v_pk_fma_f32 v[228:229], v[210:211], v[224:225], v[228:229] op_sel_hi:[1,0,1]
	v_pk_fma_f32 v[226:227], v[212:213], v[6:7], v[226:227] op_sel:[0,1,0]
	v_pk_fma_f32 v[228:229], v[212:213], v[224:225], v[228:229] op_sel:[0,1,0]
	v_pk_fma_f32 v[232:233], v[56:57], v[12:13], v[206:207] op_sel_hi:[1,0,1]
	v_add_f32_dpp v230, v227, v226 row_ror:8 row_mask:0xf bank_mask:0xf
	v_pk_fma_f32 v[234:235], v[56:57], v[12:13], v[208:209] op_sel:[0,1,0]
	v_pk_fma_f32 v[236:237], v[56:57], v[14:15], v[210:211] op_sel_hi:[1,0,1]
	v_add_f32_dpp v230, v230, v230 quad_perm:[1,0,3,2] row_mask:0xf bank_mask:0xf
	v_pk_fma_f32 v[238:239], v[56:57], v[14:15], v[212:213] op_sel:[0,1,0]
	ds_read_b128 v[222:225], v240 offset:37264
	v_add_f32_dpp v230, v230, v230 quad_perm:[2,3,0,1] row_mask:0xf bank_mask:0xf
	ds_read_b128 v[114:117], v240 offset:28832
	ds_read_b128 v[110:113], v240 offset:20128
	v_add_f32_dpp v230, v230, v230 row_half_mirror row_mask:0xf bank_mask:0xf
	ds_write_b64 v217, v[228:229] offset:4032
	ds_read_b128 v[106:109], v240 offset:11424
	v_mov_b32_dpp v231, v230 row_ror:8 row_mask:0xf bank_mask:0xf
	v_pk_fma_f32 v[206:207], v[8:9], v[230:231], v[232:233] op_sel_hi:[0,1,1] neg_lo:[1,0,0] neg_hi:[1,0,0]
	v_pk_fma_f32 v[208:209], v[8:9], v[230:231], v[234:235] op_sel:[1,0,0] neg_lo:[1,0,0] neg_hi:[1,0,0]
	v_pk_fma_f32 v[210:211], v[10:11], v[230:231], v[236:237] op_sel_hi:[0,1,1] neg_lo:[1,0,0] neg_hi:[1,0,0]
	v_pk_fma_f32 v[212:213], v[10:11], v[230:231], v[238:239] op_sel:[1,0,0] neg_lo:[1,0,0] neg_hi:[1,0,0]
	s_waitcnt lgkmcnt(6)
; template <int CTRL> __device__ __forceinline__ float dppf(float x) { return __builtin_bit_cast(float, __builtin_amdgcn_update_dpp(0, __builtin_bit_cast(int, x), CTRL, 0xF, 0xF, false)); }
; __device__ __forceinline__ void phase_rwkv_scan(const Fr& F, int jr) {
;     ...
;                 for (int pg = 0; pg < 64; pg += 16) {
; #pragma unroll
;                     for (int pi = 0; pi < 16; ++pi) {
;                         const int p = pg + pi, pn = p < 63 ? p + 1 : 63;
;                         const f32x4 w4n = PW[pn * 16], k4n = PW[1024 + pn * 16], b4n = PW[2048 + pn * 16], d4n = PW[3072 + pn * 16], r4n = PR[pn * 16];
;                         const float vvn = PV[pn * 32];
;                         f32x2 t = S01 * k4.xy; t = S23 * k4.zw + t; float sa = t.x + t.y;
;                         sa += dppf<0x128>(sa);
;                         const f32x2 dv01 = d4.xy * vv, dv23 = d4.zw * vv;
;                         sa += dppf<0x124>(sa);
;                         const f32x2 e01 = S01 * w4.xy + dv01;
;                         sa += dppf<0x122>(sa);
;                         const f32x2 e23 = S23 * w4.zw + dv23;
;                         sa += dppf<0x121>(sa);
;                         S01 = e01 - b4.xy * sa; S23 = e23 - b4.zw * sa;
;                         f32x2 u = S01 * r4.xy; u = S23 * r4.zw + u;
;                         PY[pi * 64] = u.x + u.y;
;                         w4 = w4n; k4 = k4n; b4 = b4n; d4 = d4n; r4 = r4n; vv = vvn;
;                     }
	v_pk_mul_f32 v[226:227], v[206:207], v[84:85] op_sel_hi:[1,0]
	v_pk_mul_f32 v[228:229], v[206:207], v[96:97] op_sel_hi:[1,0]
	v_pk_fma_f32 v[226:227], v[208:209], v[84:85], v[226:227] op_sel:[0,1,0]
	v_pk_fma_f32 v[228:229], v[208:209], v[96:97], v[228:229] op_sel:[0,1,0]
	v_pk_fma_f32 v[226:227], v[210:211], v[86:87], v[226:227] op_sel_hi:[1,0,1]
	v_pk_fma_f32 v[228:229], v[210:211], v[98:99], v[228:229] op_sel_hi:[1,0,1]
	v_pk_fma_f32 v[226:227], v[212:213], v[86:87], v[226:227] op_sel:[0,1,0]
	v_pk_fma_f32 v[228:229], v[212:213], v[98:99], v[228:229] op_sel:[0,1,0]
	v_pk_fma_f32 v[232:233], v[58:59], v[92:93], v[206:207] op_sel_hi:[1,0,1]
	v_add_f32_dpp v230, v227, v226 row_ror:8 row_mask:0xf bank_mask:0xf
	v_pk_fma_f32 v[234:235], v[58:59], v[92:93], v[208:209] op_sel:[0,1,0]
	v_pk_fma_f32 v[236:237], v[58:59], v[94:95], v[210:211] op_sel_hi:[1,0,1]
	v_add_f32_dpp v230, v230, v230 quad_perm:[1,0,3,2] row_mask:0xf bank_mask:0xf
	v_pk_fma_f32 v[238:239], v[58:59], v[94:95], v[212:213] op_sel:[0,1,0]
	ds_read_b128 v[96:99], v240 offset:37536
	v_add_f32_dpp v230, v230, v230 quad_perm:[2,3,0,1] row_mask:0xf bank_mask:0xf
	ds_read_b128 v[12:15], v240 offset:29104
	ds_read_b128 v[8:11], v240 offset:20400
	v_add_f32_dpp v230, v230, v230 row_half_mirror row_mask:0xf bank_mask:0xf
	ds_write_b64 v217, v[228:229] offset:4608
	ds_read_b128 v[4:7], v240 offset:11696
	v_mov_b32_dpp v231, v230 row_ror:8 row_mask:0xf bank_mask:0xf
	v_pk_fma_f32 v[206:207], v[88:89], v[230:231], v[232:233] op_sel_hi:[0,1,1] neg_lo:[1,0,0] neg_hi:[1,0,0]
	v_pk_fma_f32 v[208:209], v[88:89], v[230:231], v[234:235] op_sel:[1,0,0] neg_lo:[1,0,0] neg_hi:[1,0,0]
	v_pk_fma_f32 v[210:211], v[90:91], v[230:231], v[236:237] op_sel_hi:[0,1,1] neg_lo:[1,0,0] neg_hi:[1,0,0]
	v_pk_fma_f32 v[212:213], v[90:91], v[230:231], v[238:239] op_sel:[1,0,0] neg_lo:[1,0,0] neg_hi:[1,0,0]
	s_waitcnt lgkmcnt(5)
	ds_read_b128 v[56:59], v242 offset:46688
	v_pk_mul_f32 v[226:227], v[206:207], v[106:107] op_sel_hi:[1,0]
	v_pk_mul_f32 v[228:229], v[206:207], v[222:223] op_sel_hi:[1,0]
	v_pk_fma_f32 v[226:227], v[208:209], v[106:107], v[226:227] op_sel:[0,1,0]
	v_pk_fma_f32 v[228:229], v[208:209], v[222:223], v[228:229] op_sel:[0,1,0]
	v_pk_fma_f32 v[226:227], v[210:211], v[108:109], v[226:227] op_sel_hi:[1,0,1]
	v_pk_fma_f32 v[228:229], v[210:211], v[224:225], v[228:229] op_sel_hi:[1,0,1]
	v_pk_fma_f32 v[226:227], v[212:213], v[108:109], v[226:227] op_sel:[0,1,0]
	v_pk_fma_f32 v[228:229], v[212:213], v[224:225], v[228:229] op_sel:[0,1,0]
	v_pk_fma_f32 v[232:233], v[60:61], v[114:115], v[206:207] op_sel_hi:[1,0,1]
	v_add_f32_dpp v230, v227, v226 row_ror:8 row_mask:0xf bank_mask:0xf
	v_pk_fma_f32 v[234:235], v[60:61], v[114:115], v[208:209] op_sel:[0,1,0]
	v_pk_fma_f32 v[236:237], v[60:61], v[116:117], v[210:211] op_sel_hi:[1,0,1]
	v_add_f32_dpp v230, v230, v230 quad_perm:[1,0,3,2] row_mask:0xf bank_mask:0xf
	v_pk_fma_f32 v[238:239], v[60:61], v[116:117], v[212:213] op_sel:[0,1,0]
	ds_read_b128 v[222:225], v240 offset:37808
	v_add_f32_dpp v230, v230, v230 quad_perm:[2,3,0,1] row_mask:0xf bank_mask:0xf
	ds_read_b128 v[92:95], v240 offset:29376
	ds_read_b128 v[88:91], v240 offset:20672
	v_add_f32_dpp v230, v230, v230 row_half_mirror row_mask:0xf bank_mask:0xf
	ds_write_b64 v217, v[228:229] offset:5184
	ds_read_b128 v[84:87], v240 offset:11968
	v_mov_b32_dpp v231, v230 row_ror:8 row_mask:0xf bank_mask:0xf
	v_pk_fma_f32 v[206:207], v[110:111], v[230:231], v[232:233] op_sel_hi:[0,1,1] neg_lo:[1,0,0] neg_hi:[1,0,0]
	v_pk_fma_f32 v[208:209], v[110:111], v[230:231], v[234:235] op_sel:[1,0,0] neg_lo:[1,0,0] neg_hi:[1,0,0]
	v_pk_fma_f32 v[210:211], v[112:113], v[230:231], v[236:237] op_sel_hi:[0,1,1] neg_lo:[1,0,0] neg_hi:[1,0,0]
	v_pk_fma_f32 v[212:213], v[112:113], v[230:231], v[238:239] op_sel:[1,0,0] neg_lo:[1,0,0] neg_hi:[1,0,0]
	s_waitcnt lgkmcnt(6)
	v_pk_mul_f32 v[226:227], v[206:207], v[4:5] op_sel_hi:[1,0]
	v_pk_mul_f32 v[228:229], v[206:207], v[96:97] op_sel_hi:[1,0]
	v_pk_fma_f32 v[226:227], v[208:209], v[4:5], v[226:227] op_sel:[0,1,0]
	v_pk_fma_f32 v[228:229], v[208:209], v[96:97], v[228:229] op_sel:[0,1,0]
	v_pk_fma_f32 v[226:227], v[210:211], v[6:7], v[226:227] op_sel_hi:[1,0,1]
	v_pk_fma_f32 v[228:229], v[210:211], v[98:99], v[228:229] op_sel_hi:[1,0,1]
	v_pk_fma_f32 v[226:227], v[212:213], v[6:7], v[226:227] op_sel:[0,1,0]
	v_pk_fma_f32 v[228:229], v[212:213], v[98:99], v[228:229] op_sel:[0,1,0]
	v_pk_fma_f32 v[232:233], v[62:63], v[12:13], v[206:207] op_sel_hi:[1,0,1]
	v_add_f32_dpp v230, v227, v226 row_ror:8 row_mask:0xf bank_mask:0xf
	v_pk_fma_f32 v[234:235], v[62:63], v[12:13], v[208:209] op_sel:[0,1,0]
	v_pk_fma_f32 v[236:237], v[62:63], v[14:15], v[210:211] op_sel_hi:[1,0,1]
	v_add_f32_dpp v230, v230, v230 quad_perm:[1,0,3,2] row_mask:0xf bank_mask:0xf
	v_pk_fma_f32 v[238:239], v[62:63], v[14:15], v[212:213] op_sel:[0,1,0]
	ds_read_b128 v[96:99], v240 offset:38080
	v_add_f32_dpp v230, v230, v230 quad_perm:[2,3,0,1] row_mask:0xf bank_mask:0xf
	ds_read_b128 v[114:117], v240 offset:29648
	ds_read_b128 v[110:113], v240 offset:20944
	v_add_f32_dpp v230, v230, v230 row_half_mirror row_mask:0xf bank_mask:0xf
	ds_write_b64 v217, v[228:229] offset:5760
	ds_read_b128 v[106:109], v240 offset:12240
	v_mov_b32_dpp v231, v230 row_ror:8 row_mask:0xf bank_mask:0xf
	v_pk_fma_f32 v[206:207], v[8:9], v[230:231], v[232:233] op_sel_hi:[0,1,1] neg_lo:[1,0,0] neg_hi:[1,0,0]
	v_pk_fma_f32 v[208:209], v[8:9], v[230:231], v[234:235] op_sel:[1,0,0] neg_lo:[1,0,0] neg_hi:[1,0,0]
	v_pk_fma_f32 v[210:211], v[10:11], v[230:231], v[236:237] op_sel_hi:[0,1,1] neg_lo:[1,0,0] neg_hi:[1,0,0]
	v_pk_fma_f32 v[212:213], v[10:11], v[230:231], v[238:239] op_sel:[1,0,0] neg_lo:[1,0,0] neg_hi:[1,0,0]
	s_waitcnt lgkmcnt(5)
; template <int CTRL> __device__ __forceinline__ float dppf(float x) { return __builtin_bit_cast(float, __builtin_amdgcn_update_dpp(0, __builtin_bit_cast(int, x), CTRL, 0xF, 0xF, false)); }
; __device__ __forceinline__ void phase_rwkv_scan(const Fr& F, int jr) {
;     ...
;                 for (int pg = 0; pg < 64; pg += 16) {
; #pragma unroll
;                     for (int pi = 0; pi < 16; ++pi) {
;                         const int p = pg + pi, pn = p < 63 ? p + 1 : 63;
;                         const f32x4 w4n = PW[pn * 16], k4n = PW[1024 + pn * 16], b4n = PW[2048 + pn * 16], d4n = PW[3072 + pn * 16], r4n = PR[pn * 16];
;                         const float vvn = PV[pn * 32];
;                         f32x2 t = S01 * k4.xy; t = S23 * k4.zw + t; float sa = t.x + t.y;
;                         sa += dppf<0x128>(sa);
;                         const f32x2 dv01 = d4.xy * vv, dv23 = d4.zw * vv;
;                         sa += dppf<0x124>(sa);
;                         const f32x2 e01 = S01 * w4.xy + dv01;
;                         sa += dppf<0x122>(sa);
;                         const f32x2 e23 = S23 * w4.zw + dv23;
;                         sa += dppf<0x121>(sa);
;                         S01 = e01 - b4.xy * sa; S23 = e23 - b4.zw * sa;
;                         f32x2 u = S01 * r4.xy; u = S23 * r4.zw + u;
;                         PY[pi * 64] = u.x + u.y;
;                         w4 = w4n; k4 = k4n; b4 = b4n; d4 = d4n; r4 = r4n; vv = vvn;
;                     }
	ds_read_b128 v[60:63], v242 offset:47216
	v_pk_mul_f32 v[226:227], v[206:207], v[84:85] op_sel_hi:[1,0]
	v_pk_mul_f32 v[228:229], v[206:207], v[222:223] op_sel_hi:[1,0]
	v_pk_fma_f32 v[226:227], v[208:209], v[84:85], v[226:227] op_sel:[0,1,0]
	v_pk_fma_f32 v[228:229], v[208:209], v[222:223], v[228:229] op_sel:[0,1,0]
	v_pk_fma_f32 v[226:227], v[210:211], v[86:87], v[226:227] op_sel_hi:[1,0,1]
	v_pk_fma_f32 v[228:229], v[210:211], v[224:225], v[228:229] op_sel_hi:[1,0,1]
	v_pk_fma_f32 v[226:227], v[212:213], v[86:87], v[226:227] op_sel:[0,1,0]
	v_pk_fma_f32 v[228:229], v[212:213], v[224:225], v[228:229] op_sel:[0,1,0]
	v_pk_fma_f32 v[232:233], v[56:57], v[92:93], v[206:207] op_sel_hi:[1,0,1]
	v_add_f32_dpp v230, v227, v226 row_ror:8 row_mask:0xf bank_mask:0xf
	v_pk_fma_f32 v[234:235], v[56:57], v[92:93], v[208:209] op_sel:[0,1,0]
	v_pk_fma_f32 v[236:237], v[56:57], v[94:95], v[210:211] op_sel_hi:[1,0,1]
	v_add_f32_dpp v230, v230, v230 quad_perm:[1,0,3,2] row_mask:0xf bank_mask:0xf
	v_pk_fma_f32 v[238:239], v[56:57], v[94:95], v[212:213] op_sel:[0,1,0]
	ds_read_b128 v[222:225], v240 offset:38352
	v_add_f32_dpp v230, v230, v230 quad_perm:[2,3,0,1] row_mask:0xf bank_mask:0xf
	ds_read_b128 v[12:15], v240 offset:29920
	ds_read_b128 v[8:11], v240 offset:21216
	v_add_f32_dpp v230, v230, v230 row_half_mirror row_mask:0xf bank_mask:0xf
	ds_write_b64 v217, v[228:229] offset:6336
	ds_read_b128 v[4:7], v240 offset:12512
	v_mov_b32_dpp v231, v230 row_ror:8 row_mask:0xf bank_mask:0xf
	v_pk_fma_f32 v[206:207], v[88:89], v[230:231], v[232:233] op_sel_hi:[0,1,1] neg_lo:[1,0,0] neg_hi:[1,0,0]
	v_pk_fma_f32 v[208:209], v[88:89], v[230:231], v[234:235] op_sel:[1,0,0] neg_lo:[1,0,0] neg_hi:[1,0,0]
	v_pk_fma_f32 v[210:211], v[90:91], v[230:231], v[236:237] op_sel_hi:[0,1,1] neg_lo:[1,0,0] neg_hi:[1,0,0]
	v_pk_fma_f32 v[212:213], v[90:91], v[230:231], v[238:239] op_sel:[1,0,0] neg_lo:[1,0,0] neg_hi:[1,0,0]
	s_waitcnt lgkmcnt(6)
	v_pk_mul_f32 v[226:227], v[206:207], v[106:107] op_sel_hi:[1,0]
	v_pk_mul_f32 v[228:229], v[206:207], v[96:97] op_sel_hi:[1,0]
	v_pk_fma_f32 v[226:227], v[208:209], v[106:107], v[226:227] op_sel:[0,1,0]
	v_pk_fma_f32 v[228:229], v[208:209], v[96:97], v[228:229] op_sel:[0,1,0]
	v_pk_fma_f32 v[226:227], v[210:211], v[108:109], v[226:227] op_sel_hi:[1,0,1]
	v_pk_fma_f32 v[228:229], v[210:211], v[98:99], v[228:229] op_sel_hi:[1,0,1]
	v_pk_fma_f32 v[226:227], v[212:213], v[108:109], v[226:227] op_sel:[0,1,0]
	v_pk_fma_f32 v[228:229], v[212:213], v[98:99], v[228:229] op_sel:[0,1,0]
	v_pk_fma_f32 v[232:233], v[58:59], v[114:115], v[206:207] op_sel_hi:[1,0,1]
	v_add_f32_dpp v230, v227, v226 row_ror:8 row_mask:0xf bank_mask:0xf
	v_pk_fma_f32 v[234:235], v[58:59], v[114:115], v[208:209] op_sel:[0,1,0]
	v_pk_fma_f32 v[236:237], v[58:59], v[116:117], v[210:211] op_sel_hi:[1,0,1]
	v_add_f32_dpp v230, v230, v230 quad_perm:[1,0,3,2] row_mask:0xf bank_mask:0xf
	v_pk_fma_f32 v[238:239], v[58:59], v[116:117], v[212:213] op_sel:[0,1,0]
	ds_read_b128 v[96:99], v240 offset:38624
	v_add_f32_dpp v230, v230, v230 quad_perm:[2,3,0,1] row_mask:0xf bank_mask:0xf
	ds_read_b128 v[92:95], v240 offset:30192
	ds_read_b128 v[88:91], v240 offset:21488
	v_add_f32_dpp v230, v230, v230 row_half_mirror row_mask:0xf bank_mask:0xf
	ds_write_b64 v217, v[228:229] offset:6912
	ds_read_b128 v[84:87], v240 offset:12784
	ds_read_b128 v[80:83], v240 offset:4080
	v_mov_b32_dpp v231, v230 row_ror:8 row_mask:0xf bank_mask:0xf
	v_pk_fma_f32 v[206:207], v[110:111], v[230:231], v[232:233] op_sel_hi:[0,1,1] neg_lo:[1,0,0] neg_hi:[1,0,0]
	v_pk_fma_f32 v[208:209], v[110:111], v[230:231], v[234:235] op_sel:[1,0,0] neg_lo:[1,0,0] neg_hi:[1,0,0]
	v_pk_fma_f32 v[210:211], v[112:113], v[230:231], v[236:237] op_sel_hi:[0,1,1] neg_lo:[1,0,0] neg_hi:[1,0,0]
	v_pk_fma_f32 v[212:213], v[112:113], v[230:231], v[238:239] op_sel:[1,0,0] neg_lo:[1,0,0] neg_hi:[1,0,0]
	s_waitcnt lgkmcnt(6)
	ds_read_b128 v[56:59], v242 offset:47744
	v_pk_mul_f32 v[226:227], v[206:207], v[4:5] op_sel_hi:[1,0]
	v_pk_mul_f32 v[228:229], v[206:207], v[222:223] op_sel_hi:[1,0]
	v_pk_fma_f32 v[226:227], v[208:209], v[4:5], v[226:227] op_sel:[0,1,0]
	v_pk_fma_f32 v[228:229], v[208:209], v[222:223], v[228:229] op_sel:[0,1,0]
	v_pk_fma_f32 v[226:227], v[210:211], v[6:7], v[226:227] op_sel_hi:[1,0,1]
	v_pk_fma_f32 v[228:229], v[210:211], v[224:225], v[228:229] op_sel_hi:[1,0,1]
	v_pk_fma_f32 v[226:227], v[212:213], v[6:7], v[226:227] op_sel:[0,1,0]
	v_pk_fma_f32 v[228:229], v[212:213], v[224:225], v[228:229] op_sel:[0,1,0]
	v_pk_fma_f32 v[232:233], v[60:61], v[12:13], v[206:207] op_sel_hi:[1,0,1]
	v_add_f32_dpp v230, v227, v226 row_ror:8 row_mask:0xf bank_mask:0xf
	v_pk_fma_f32 v[234:235], v[60:61], v[12:13], v[208:209] op_sel:[0,1,0]
	v_pk_fma_f32 v[236:237], v[60:61], v[14:15], v[210:211] op_sel_hi:[1,0,1]
	v_add_f32_dpp v230, v230, v230 quad_perm:[1,0,3,2] row_mask:0xf bank_mask:0xf
	v_pk_fma_f32 v[238:239], v[60:61], v[14:15], v[212:213] op_sel:[0,1,0]
	ds_read_b128 v[222:225], v240 offset:38896
	v_add_f32_dpp v230, v230, v230 quad_perm:[2,3,0,1] row_mask:0xf bank_mask:0xf
	ds_read_b128 v[114:117], v240 offset:30464
	ds_read_b128 v[110:113], v240 offset:21760
	v_add_f32_dpp v230, v230, v230 row_half_mirror row_mask:0xf bank_mask:0xf
	ds_write_b64 v217, v[228:229] offset:7488
	ds_read_b128 v[106:109], v240 offset:13056
	v_mov_b32_dpp v231, v230 row_ror:8 row_mask:0xf bank_mask:0xf
	v_pk_fma_f32 v[206:207], v[8:9], v[230:231], v[232:233] op_sel_hi:[0,1,1] neg_lo:[1,0,0] neg_hi:[1,0,0]
	v_pk_fma_f32 v[208:209], v[8:9], v[230:231], v[234:235] op_sel:[1,0,0] neg_lo:[1,0,0] neg_hi:[1,0,0]
	v_pk_fma_f32 v[210:211], v[10:11], v[230:231], v[236:237] op_sel_hi:[0,1,1] neg_lo:[1,0,0] neg_hi:[1,0,0]
	v_pk_fma_f32 v[212:213], v[10:11], v[230:231], v[238:239] op_sel:[1,0,0] neg_lo:[1,0,0] neg_hi:[1,0,0]
	s_waitcnt lgkmcnt(7)
; __device__ __forceinline__ unsigned f2bf(float f) { unsigned u = __builtin_bit_cast(unsigned, f); return (u + 0x7fffu + ((u >> 16) & 1u)) >> 16; }
; template <int CTRL> __device__ __forceinline__ float dppf(float x) { return __builtin_bit_cast(float, __builtin_amdgcn_update_dpp(0, __builtin_bit_cast(int, x), CTRL, 0xF, 0xF, false)); }
; __device__ __forceinline__ void phase_rwkv_scan(const Fr& F, int jr) {
;     ...
;                     for (int pi = 0; pi < 16; ++pi) {
;                         const int p = pg + pi, pn = p < 63 ? p + 1 : 63;
;                         const f32x4 w4n = PW[pn * 16], k4n = PW[1024 + pn * 16], b4n = PW[2048 + pn * 16], d4n = PW[3072 + pn * 16], r4n = PR[pn * 16];
;                         const float vvn = PV[pn * 32];
;                         f32x2 t = S01 * k4.xy; t = S23 * k4.zw + t; float sa = t.x + t.y;
;                         sa += dppf<0x128>(sa);
;                         const f32x2 dv01 = d4.xy * vv, dv23 = d4.zw * vv;
;                         sa += dppf<0x124>(sa);
;                         const f32x2 e01 = S01 * w4.xy + dv01;
;                         sa += dppf<0x122>(sa);
;                         const f32x2 e23 = S23 * w4.zw + dv23;
;                         sa += dppf<0x121>(sa);
;                         S01 = e01 - b4.xy * sa; S23 = e23 - b4.zw * sa;
;                         f32x2 u = S01 * r4.xy; u = S23 * r4.zw + u;
;                         PY[pi * 64] = u.x + u.y;
;                         w4 = w4n; k4 = k4n; b4 = b4n; d4 = d4n; r4 = r4n; vv = vvn;
;                     }
;                     asm volatile("s_waitcnt lgkmcnt(0)" ::: "memory");
;                     {
;                         const int j = lane >> 2, q = lane & 3; const float* yp = Ypw + j * 64 + q * 16;
;                         const f32x4 a0 = *(const f32x4*)yp, a1 = *(const f32x4*)(yp + 4), a2 = *(const f32x4*)(yp + 8), a3 = *(const f32x4*)(yp + 12);
;                         const f32x4 ssum = (a0 + a1) + (a2 + a3); const float yv = (ssum.x + ssum.y) + (ssum.z + ssum.w);
;                         const size_t row = (size_t)b * TB + tokof(s, chunk * 64 + pg + j);
;                         Yb[row * D + h * 64 + 32 * half + 4 * wave + q] = (bf16)f2bf(yv);
;                     }
	v_pk_mul_f32 v[226:227], v[206:207], v[84:85] op_sel_hi:[1,0]
	v_pk_mul_f32 v[228:229], v[206:207], v[96:97] op_sel_hi:[1,0]
	v_pk_fma_f32 v[226:227], v[208:209], v[84:85], v[226:227] op_sel:[0,1,0]
	v_pk_fma_f32 v[228:229], v[208:209], v[96:97], v[228:229] op_sel:[0,1,0]
	v_pk_fma_f32 v[226:227], v[210:211], v[86:87], v[226:227] op_sel_hi:[1,0,1]
	v_pk_fma_f32 v[228:229], v[210:211], v[98:99], v[228:229] op_sel_hi:[1,0,1]
	v_pk_fma_f32 v[226:227], v[212:213], v[86:87], v[226:227] op_sel:[0,1,0]
	v_pk_fma_f32 v[228:229], v[212:213], v[98:99], v[228:229] op_sel:[0,1,0]
	v_pk_fma_f32 v[232:233], v[62:63], v[92:93], v[206:207] op_sel_hi:[1,0,1]
	v_add_f32_dpp v230, v227, v226 row_ror:8 row_mask:0xf bank_mask:0xf
	v_pk_fma_f32 v[234:235], v[62:63], v[92:93], v[208:209] op_sel:[0,1,0]
	v_pk_fma_f32 v[236:237], v[62:63], v[94:95], v[210:211] op_sel_hi:[1,0,1]
	v_add_f32_dpp v230, v230, v230 quad_perm:[1,0,3,2] row_mask:0xf bank_mask:0xf
	v_pk_fma_f32 v[238:239], v[62:63], v[94:95], v[212:213] op_sel:[0,1,0]
	ds_read_b128 v[96:99], v240 offset:39168
	v_add_f32_dpp v230, v230, v230 quad_perm:[2,3,0,1] row_mask:0xf bank_mask:0xf
	ds_read_b128 v[12:15], v240 offset:30736
	ds_read_b128 v[8:11], v240 offset:22032
	v_add_f32_dpp v230, v230, v230 row_half_mirror row_mask:0xf bank_mask:0xf
	ds_write_b64 v217, v[228:229] offset:8064
	ds_read_b128 v[4:7], v240 offset:13328
	v_mov_b32_dpp v231, v230 row_ror:8 row_mask:0xf bank_mask:0xf
	v_pk_fma_f32 v[206:207], v[88:89], v[230:231], v[232:233] op_sel_hi:[0,1,1] neg_lo:[1,0,0] neg_hi:[1,0,0]
	v_pk_fma_f32 v[208:209], v[88:89], v[230:231], v[234:235] op_sel:[1,0,0] neg_lo:[1,0,0] neg_hi:[1,0,0]
	v_pk_fma_f32 v[210:211], v[90:91], v[230:231], v[236:237] op_sel_hi:[0,1,1] neg_lo:[1,0,0] neg_hi:[1,0,0]
	v_pk_fma_f32 v[212:213], v[90:91], v[230:231], v[238:239] op_sel:[1,0,0] neg_lo:[1,0,0] neg_hi:[1,0,0]
	s_waitcnt lgkmcnt(9)
	v_pk_mul_f32 v[228:229], v[206:207], v[222:223] op_sel_hi:[1,0]
	v_add_u32_e32 v243, s15, v219
	v_pk_fma_f32 v[228:229], v[208:209], v[222:223], v[228:229] op_sel:[0,1,0]
	v_lshl_add_u32 v243, v243, 11, v220
	v_pk_fma_f32 v[228:229], v[210:211], v[224:225], v[228:229] op_sel_hi:[1,0,1]
	v_pk_fma_f32 v[228:229], v[212:213], v[224:225], v[228:229] op_sel:[0,1,0]
	s_waitcnt lgkmcnt(6)
	ds_write_b64 v217, v[228:229] offset:8640
	v_pk_mul_f32 v[206:207], v[206:207], v[80:81] op_sel_hi:[1,0]
	v_pk_mul_f32 v[208:209], v[208:209], v[80:81] op_sel:[0,1]
	v_pk_mul_f32 v[210:211], v[210:211], v[82:83] op_sel_hi:[1,0]
	v_pk_mul_f32 v[212:213], v[212:213], v[82:83] op_sel:[0,1]
	ds_read_b128 v[24:27], v218 offset:0
	ds_read_b128 v[28:31], v218 offset:16
	ds_read_b128 v[32:35], v218 offset:32
	ds_read_b128 v[36:39], v218 offset:48
	ds_read_b128 v[40:43], v218 offset:64
	ds_read_b128 v[44:47], v218 offset:80
	ds_read_b128 v[48:51], v218 offset:96
	ds_read_b128 v[52:55], v218 offset:112
	s_waitcnt lgkmcnt(4)
	v_pk_add_f32 v[24:25], v[24:25], v[26:27]
	v_pk_add_f32 v[28:29], v[28:29], v[30:31]
	v_pk_add_f32 v[32:33], v[32:33], v[34:35]
	v_pk_add_f32 v[36:37], v[36:37], v[38:39]
	v_pk_add_f32 v[24:25], v[24:25], v[28:29]
	s_waitcnt lgkmcnt(0)
	v_pk_add_f32 v[40:41], v[40:41], v[42:43]
	v_pk_add_f32 v[44:45], v[44:45], v[46:47]
	v_pk_add_f32 v[32:33], v[32:33], v[36:37]
	v_pk_add_f32 v[48:49], v[48:49], v[50:51]
	v_pk_add_f32 v[52:53], v[52:53], v[54:55]
	v_pk_add_f32 v[40:41], v[40:41], v[44:45]
	v_pk_add_f32 v[24:25], v[24:25], v[32:33]
	v_pk_add_f32 v[48:49], v[48:49], v[52:53]
	s_add_i32 s15, s15, s19
	v_pk_add_f32 v[40:41], v[40:41], v[48:49]
	v_pk_add_f32 v[24:25], v[24:25], v[40:41] op_sel:[0,1] op_sel_hi:[1,0]
	v_cvt_pk_bf16_f32 v244, v24, v25
	global_store_dword v243, v244, s[20:21]
	v_pk_mul_f32 v[226:227], v[206:207], v[106:107] op_sel_hi:[1,0]
	v_pk_fma_f32 v[232:233], v[56:57], v[114:115], v[206:207] op_sel_hi:[1,0,1]
	v_pk_fma_f32 v[226:227], v[208:209], v[106:107], v[226:227] op_sel:[0,1,0]
	v_pk_fma_f32 v[234:235], v[56:57], v[114:115], v[208:209] op_sel:[0,1,0]
	v_pk_fma_f32 v[226:227], v[210:211], v[108:109], v[226:227] op_sel_hi:[1,0,1]
	v_pk_fma_f32 v[236:237], v[56:57], v[116:117], v[210:211] op_sel_hi:[1,0,1]
	v_pk_fma_f32 v[226:227], v[212:213], v[108:109], v[226:227] op_sel:[0,1,0]
	v_pk_fma_f32 v[238:239], v[56:57], v[116:117], v[212:213] op_sel:[0,1,0]
	ds_read_b128 v[92:95], v240 offset:31008
	v_add_f32_dpp v230, v227, v226 row_ror:8 row_mask:0xf bank_mask:0xf
	ds_read_b128 v[88:91], v240 offset:22304
	ds_read_b128 v[84:87], v240 offset:13600
	v_add_f32_dpp v230, v230, v230 quad_perm:[1,0,3,2] row_mask:0xf bank_mask:0xf
	ds_read_b128 v[222:225], v240 offset:39440
	ds_read_b128 v[60:63], v242 offset:48272
	v_add_f32_dpp v230, v230, v230 quad_perm:[2,3,0,1] row_mask:0xf bank_mask:0xf
	s_nop 1
	v_add_f32_dpp v230, v230, v230 row_half_mirror row_mask:0xf bank_mask:0xf
	s_nop 1
	v_mov_b32_dpp v231, v230 row_ror:8 row_mask:0xf bank_mask:0xf
	v_pk_fma_f32 v[206:207], v[110:111], v[230:231], v[232:233] op_sel_hi:[0,1,1] neg_lo:[1,0,0] neg_hi:[1,0,0]
	v_pk_fma_f32 v[208:209], v[110:111], v[230:231], v[234:235] op_sel:[1,0,0] neg_lo:[1,0,0] neg_hi:[1,0,0]
	v_pk_fma_f32 v[210:211], v[112:113], v[230:231], v[236:237] op_sel_hi:[0,1,1] neg_lo:[1,0,0] neg_hi:[1,0,0]
	v_pk_fma_f32 v[212:213], v[112:113], v[230:231], v[238:239] op_sel:[1,0,0] neg_lo:[1,0,0] neg_hi:[1,0,0]
	v_pk_mul_f32 v[226:227], v[206:207], v[4:5] op_sel_hi:[1,0]
	v_pk_mul_f32 v[228:229], v[206:207], v[96:97] op_sel_hi:[1,0]
	v_pk_fma_f32 v[226:227], v[208:209], v[4:5], v[226:227] op_sel:[0,1,0]
	v_pk_fma_f32 v[228:229], v[208:209], v[96:97], v[228:229] op_sel:[0,1,0]
	v_pk_fma_f32 v[226:227], v[210:211], v[6:7], v[226:227] op_sel_hi:[1,0,1]
; template <int CTRL> __device__ __forceinline__ float dppf(float x) { return __builtin_bit_cast(float, __builtin_amdgcn_update_dpp(0, __builtin_bit_cast(int, x), CTRL, 0xF, 0xF, false)); }
; __device__ __forceinline__ void phase_rwkv_scan(const Fr& F, int jr) {
;     ...
;                 for (int pg = 0; pg < 64; pg += 16) {
; #pragma unroll
;                     for (int pi = 0; pi < 16; ++pi) {
;                         const int p = pg + pi, pn = p < 63 ? p + 1 : 63;
;                         const f32x4 w4n = PW[pn * 16], k4n = PW[1024 + pn * 16], b4n = PW[2048 + pn * 16], d4n = PW[3072 + pn * 16], r4n = PR[pn * 16];
;                         const float vvn = PV[pn * 32];
;                         f32x2 t = S01 * k4.xy; t = S23 * k4.zw + t; float sa = t.x + t.y;
;                         sa += dppf<0x128>(sa);
;                         const f32x2 dv01 = d4.xy * vv, dv23 = d4.zw * vv;
;                         sa += dppf<0x124>(sa);
;                         const f32x2 e01 = S01 * w4.xy + dv01;
;                         sa += dppf<0x122>(sa);
;                         const f32x2 e23 = S23 * w4.zw + dv23;
;                         sa += dppf<0x121>(sa);
;                         S01 = e01 - b4.xy * sa; S23 = e23 - b4.zw * sa;
;                         f32x2 u = S01 * r4.xy; u = S23 * r4.zw + u;
;                         PY[pi * 64] = u.x + u.y;
;                         w4 = w4n; k4 = k4n; b4 = b4n; d4 = d4n; r4 = r4n; vv = vvn;
;                     }
	v_pk_fma_f32 v[228:229], v[210:211], v[98:99], v[228:229] op_sel_hi:[1,0,1]
	v_pk_fma_f32 v[226:227], v[212:213], v[6:7], v[226:227] op_sel:[0,1,0]
	v_pk_fma_f32 v[228:229], v[212:213], v[98:99], v[228:229] op_sel:[0,1,0]
	v_pk_fma_f32 v[232:233], v[58:59], v[12:13], v[206:207] op_sel_hi:[1,0,1]
	v_add_f32_dpp v230, v227, v226 row_ror:8 row_mask:0xf bank_mask:0xf
	v_pk_fma_f32 v[234:235], v[58:59], v[12:13], v[208:209] op_sel:[0,1,0]
	v_pk_fma_f32 v[236:237], v[58:59], v[14:15], v[210:211] op_sel_hi:[1,0,1]
	v_add_f32_dpp v230, v230, v230 quad_perm:[1,0,3,2] row_mask:0xf bank_mask:0xf
	v_pk_fma_f32 v[238:239], v[58:59], v[14:15], v[212:213] op_sel:[0,1,0]
	ds_read_b128 v[96:99], v240 offset:39712
	v_add_f32_dpp v230, v230, v230 quad_perm:[2,3,0,1] row_mask:0xf bank_mask:0xf
	ds_read_b128 v[114:117], v240 offset:31280
	ds_read_b128 v[110:113], v240 offset:22576
	v_add_f32_dpp v230, v230, v230 row_half_mirror row_mask:0xf bank_mask:0xf
	ds_write_b64 v217, v[228:229] offset:0
	ds_read_b128 v[106:109], v240 offset:13872
	v_mov_b32_dpp v231, v230 row_ror:8 row_mask:0xf bank_mask:0xf
	v_pk_fma_f32 v[206:207], v[8:9], v[230:231], v[232:233] op_sel_hi:[0,1,1] neg_lo:[1,0,0] neg_hi:[1,0,0]
	v_pk_fma_f32 v[208:209], v[8:9], v[230:231], v[234:235] op_sel:[1,0,0] neg_lo:[1,0,0] neg_hi:[1,0,0]
	v_pk_fma_f32 v[210:211], v[10:11], v[230:231], v[236:237] op_sel_hi:[0,1,1] neg_lo:[1,0,0] neg_hi:[1,0,0]
	v_pk_fma_f32 v[212:213], v[10:11], v[230:231], v[238:239] op_sel:[1,0,0] neg_lo:[1,0,0] neg_hi:[1,0,0]
	s_waitcnt lgkmcnt(5)
	ds_read_b128 v[56:59], v242 offset:48800
	v_pk_mul_f32 v[226:227], v[206:207], v[84:85] op_sel_hi:[1,0]
	v_pk_mul_f32 v[228:229], v[206:207], v[222:223] op_sel_hi:[1,0]
	v_pk_fma_f32 v[226:227], v[208:209], v[84:85], v[226:227] op_sel:[0,1,0]
	v_pk_fma_f32 v[228:229], v[208:209], v[222:223], v[228:229] op_sel:[0,1,0]
	v_pk_fma_f32 v[226:227], v[210:211], v[86:87], v[226:227] op_sel_hi:[1,0,1]
	v_pk_fma_f32 v[228:229], v[210:211], v[224:225], v[228:229] op_sel_hi:[1,0,1]
	v_pk_fma_f32 v[226:227], v[212:213], v[86:87], v[226:227] op_sel:[0,1,0]
	v_pk_fma_f32 v[228:229], v[212:213], v[224:225], v[228:229] op_sel:[0,1,0]
	v_pk_fma_f32 v[232:233], v[60:61], v[92:93], v[206:207] op_sel_hi:[1,0,1]
	v_add_f32_dpp v230, v227, v226 row_ror:8 row_mask:0xf bank_mask:0xf
	v_pk_fma_f32 v[234:235], v[60:61], v[92:93], v[208:209] op_sel:[0,1,0]
	v_pk_fma_f32 v[236:237], v[60:61], v[94:95], v[210:211] op_sel_hi:[1,0,1]
	v_add_f32_dpp v230, v230, v230 quad_perm:[1,0,3,2] row_mask:0xf bank_mask:0xf
	v_pk_fma_f32 v[238:239], v[60:61], v[94:95], v[212:213] op_sel:[0,1,0]
	ds_read_b128 v[222:225], v240 offset:39984
	v_add_f32_dpp v230, v230, v230 quad_perm:[2,3,0,1] row_mask:0xf bank_mask:0xf
	ds_read_b128 v[12:15], v240 offset:31552
	ds_read_b128 v[8:11], v240 offset:22848
	v_add_f32_dpp v230, v230, v230 row_half_mirror row_mask:0xf bank_mask:0xf
	ds_write_b64 v217, v[228:229] offset:576
	ds_read_b128 v[4:7], v240 offset:14144
	v_mov_b32_dpp v231, v230 row_ror:8 row_mask:0xf bank_mask:0xf
	v_pk_fma_f32 v[206:207], v[88:89], v[230:231], v[232:233] op_sel_hi:[0,1,1] neg_lo:[1,0,0] neg_hi:[1,0,0]
	v_pk_fma_f32 v[208:209], v[88:89], v[230:231], v[234:235] op_sel:[1,0,0] neg_lo:[1,0,0] neg_hi:[1,0,0]
	v_pk_fma_f32 v[210:211], v[90:91], v[230:231], v[236:237] op_sel_hi:[0,1,1] neg_lo:[1,0,0] neg_hi:[1,0,0]
	v_pk_fma_f32 v[212:213], v[90:91], v[230:231], v[238:239] op_sel:[1,0,0] neg_lo:[1,0,0] neg_hi:[1,0,0]
	s_waitcnt lgkmcnt(6)
	v_pk_mul_f32 v[226:227], v[206:207], v[106:107] op_sel_hi:[1,0]
	v_pk_mul_f32 v[228:229], v[206:207], v[96:97] op_sel_hi:[1,0]
	v_pk_fma_f32 v[226:227], v[208:209], v[106:107], v[226:227] op_sel:[0,1,0]
	v_pk_fma_f32 v[228:229], v[208:209], v[96:97], v[228:229] op_sel:[0,1,0]
	v_pk_fma_f32 v[226:227], v[210:211], v[108:109], v[226:227] op_sel_hi:[1,0,1]
	v_pk_fma_f32 v[228:229], v[210:211], v[98:99], v[228:229] op_sel_hi:[1,0,1]
	v_pk_fma_f32 v[226:227], v[212:213], v[108:109], v[226:227] op_sel:[0,1,0]
	v_pk_fma_f32 v[228:229], v[212:213], v[98:99], v[228:229] op_sel:[0,1,0]
	v_pk_fma_f32 v[232:233], v[62:63], v[114:115], v[206:207] op_sel_hi:[1,0,1]
	v_add_f32_dpp v230, v227, v226 row_ror:8 row_mask:0xf bank_mask:0xf
	v_pk_fma_f32 v[234:235], v[62:63], v[114:115], v[208:209] op_sel:[0,1,0]
	v_pk_fma_f32 v[236:237], v[62:63], v[116:117], v[210:211] op_sel_hi:[1,0,1]
	v_add_f32_dpp v230, v230, v230 quad_perm:[1,0,3,2] row_mask:0xf bank_mask:0xf
	v_pk_fma_f32 v[238:239], v[62:63], v[116:117], v[212:213] op_sel:[0,1,0]
	ds_read_b128 v[96:99], v240 offset:40256
	v_add_f32_dpp v230, v230, v230 quad_perm:[2,3,0,1] row_mask:0xf bank_mask:0xf
	ds_read_b128 v[92:95], v240 offset:31824
	ds_read_b128 v[88:91], v240 offset:23120
	v_add_f32_dpp v230, v230, v230 row_half_mirror row_mask:0xf bank_mask:0xf
	ds_write_b64 v217, v[228:229] offset:1152
	ds_read_b128 v[84:87], v240 offset:14416
	v_mov_b32_dpp v231, v230 row_ror:8 row_mask:0xf bank_mask:0xf
	v_pk_fma_f32 v[206:207], v[110:111], v[230:231], v[232:233] op_sel_hi:[0,1,1] neg_lo:[1,0,0] neg_hi:[1,0,0]
	v_pk_fma_f32 v[208:209], v[110:111], v[230:231], v[234:235] op_sel:[1,0,0] neg_lo:[1,0,0] neg_hi:[1,0,0]
	v_pk_fma_f32 v[210:211], v[112:113], v[230:231], v[236:237] op_sel_hi:[0,1,1] neg_lo:[1,0,0] neg_hi:[1,0,0]
	v_pk_fma_f32 v[212:213], v[112:113], v[230:231], v[238:239] op_sel:[1,0,0] neg_lo:[1,0,0] neg_hi:[1,0,0]
	s_waitcnt lgkmcnt(5)
; template <int CTRL> __device__ __forceinline__ float dppf(float x) { return __builtin_bit_cast(float, __builtin_amdgcn_update_dpp(0, __builtin_bit_cast(int, x), CTRL, 0xF, 0xF, false)); }
; __device__ __forceinline__ void phase_rwkv_scan(const Fr& F, int jr) {
;     ...
;                 for (int pg = 0; pg < 64; pg += 16) {
; #pragma unroll
;                     for (int pi = 0; pi < 16; ++pi) {
;                         const int p = pg + pi, pn = p < 63 ? p + 1 : 63;
;                         const f32x4 w4n = PW[pn * 16], k4n = PW[1024 + pn * 16], b4n = PW[2048 + pn * 16], d4n = PW[3072 + pn * 16], r4n = PR[pn * 16];
;                         const float vvn = PV[pn * 32];
;                         f32x2 t = S01 * k4.xy; t = S23 * k4.zw + t; float sa = t.x + t.y;
;                         sa += dppf<0x128>(sa);
;                         const f32x2 dv01 = d4.xy * vv, dv23 = d4.zw * vv;
;                         sa += dppf<0x124>(sa);
;                         const f32x2 e01 = S01 * w4.xy + dv01;
;                         sa += dppf<0x122>(sa);
;                         const f32x2 e23 = S23 * w4.zw + dv23;
;                         sa += dppf<0x121>(sa);
;                         S01 = e01 - b4.xy * sa; S23 = e23 - b4.zw * sa;
;                         f32x2 u = S01 * r4.xy; u = S23 * r4.zw + u;
;                         PY[pi * 64] = u.x + u.y;
;                         w4 = w4n; k4 = k4n; b4 = b4n; d4 = d4n; r4 = r4n; vv = vvn;
;                     }
	ds_read_b128 v[60:63], v242 offset:49328
	v_pk_mul_f32 v[226:227], v[206:207], v[4:5] op_sel_hi:[1,0]
	v_pk_mul_f32 v[228:229], v[206:207], v[222:223] op_sel_hi:[1,0]
	v_pk_fma_f32 v[226:227], v[208:209], v[4:5], v[226:227] op_sel:[0,1,0]
	v_pk_fma_f32 v[228:229], v[208:209], v[222:223], v[228:229] op_sel:[0,1,0]
	v_pk_fma_f32 v[226:227], v[210:211], v[6:7], v[226:227] op_sel_hi:[1,0,1]
	v_pk_fma_f32 v[228:229], v[210:211], v[224:225], v[228:229] op_sel_hi:[1,0,1]
	v_pk_fma_f32 v[226:227], v[212:213], v[6:7], v[226:227] op_sel:[0,1,0]
	v_pk_fma_f32 v[228:229], v[212:213], v[224:225], v[228:229] op_sel:[0,1,0]
	v_pk_fma_f32 v[232:233], v[56:57], v[12:13], v[206:207] op_sel_hi:[1,0,1]
	v_add_f32_dpp v230, v227, v226 row_ror:8 row_mask:0xf bank_mask:0xf
	v_pk_fma_f32 v[234:235], v[56:57], v[12:13], v[208:209] op_sel:[0,1,0]
	v_pk_fma_f32 v[236:237], v[56:57], v[14:15], v[210:211] op_sel_hi:[1,0,1]
	v_add_f32_dpp v230, v230, v230 quad_perm:[1,0,3,2] row_mask:0xf bank_mask:0xf
	v_pk_fma_f32 v[238:239], v[56:57], v[14:15], v[212:213] op_sel:[0,1,0]
	ds_read_b128 v[222:225], v240 offset:40528
	v_add_f32_dpp v230, v230, v230 quad_perm:[2,3,0,1] row_mask:0xf bank_mask:0xf
	ds_read_b128 v[114:117], v240 offset:32096
	ds_read_b128 v[110:113], v240 offset:23392
	v_add_f32_dpp v230, v230, v230 row_half_mirror row_mask:0xf bank_mask:0xf
	ds_write_b64 v217, v[228:229] offset:1728
	ds_read_b128 v[106:109], v240 offset:14688
	v_mov_b32_dpp v231, v230 row_ror:8 row_mask:0xf bank_mask:0xf
	v_pk_fma_f32 v[206:207], v[8:9], v[230:231], v[232:233] op_sel_hi:[0,1,1] neg_lo:[1,0,0] neg_hi:[1,0,0]
	v_pk_fma_f32 v[208:209], v[8:9], v[230:231], v[234:235] op_sel:[1,0,0] neg_lo:[1,0,0] neg_hi:[1,0,0]
	v_pk_fma_f32 v[210:211], v[10:11], v[230:231], v[236:237] op_sel_hi:[0,1,1] neg_lo:[1,0,0] neg_hi:[1,0,0]
	v_pk_fma_f32 v[212:213], v[10:11], v[230:231], v[238:239] op_sel:[1,0,0] neg_lo:[1,0,0] neg_hi:[1,0,0]
	s_waitcnt lgkmcnt(6)
	v_pk_mul_f32 v[226:227], v[206:207], v[84:85] op_sel_hi:[1,0]
	v_pk_mul_f32 v[228:229], v[206:207], v[96:97] op_sel_hi:[1,0]
	v_pk_fma_f32 v[226:227], v[208:209], v[84:85], v[226:227] op_sel:[0,1,0]
	v_pk_fma_f32 v[228:229], v[208:209], v[96:97], v[228:229] op_sel:[0,1,0]
	v_pk_fma_f32 v[226:227], v[210:211], v[86:87], v[226:227] op_sel_hi:[1,0,1]
	v_pk_fma_f32 v[228:229], v[210:211], v[98:99], v[228:229] op_sel_hi:[1,0,1]
	v_pk_fma_f32 v[226:227], v[212:213], v[86:87], v[226:227] op_sel:[0,1,0]
	v_pk_fma_f32 v[228:229], v[212:213], v[98:99], v[228:229] op_sel:[0,1,0]
	v_pk_fma_f32 v[232:233], v[58:59], v[92:93], v[206:207] op_sel_hi:[1,0,1]
	v_add_f32_dpp v230, v227, v226 row_ror:8 row_mask:0xf bank_mask:0xf
	v_pk_fma_f32 v[234:235], v[58:59], v[92:93], v[208:209] op_sel:[0,1,0]
	v_pk_fma_f32 v[236:237], v[58:59], v[94:95], v[210:211] op_sel_hi:[1,0,1]
	v_add_f32_dpp v230, v230, v230 quad_perm:[1,0,3,2] row_mask:0xf bank_mask:0xf
	v_pk_fma_f32 v[238:239], v[58:59], v[94:95], v[212:213] op_sel:[0,1,0]
	ds_read_b128 v[96:99], v240 offset:40800
	v_add_f32_dpp v230, v230, v230 quad_perm:[2,3,0,1] row_mask:0xf bank_mask:0xf
	ds_read_b128 v[12:15], v240 offset:32368
	ds_read_b128 v[8:11], v240 offset:23664
	v_add_f32_dpp v230, v230, v230 row_half_mirror row_mask:0xf bank_mask:0xf
	ds_write_b64 v217, v[228:229] offset:2304
	ds_read_b128 v[4:7], v240 offset:14960
	v_mov_b32_dpp v231, v230 row_ror:8 row_mask:0xf bank_mask:0xf
	v_pk_fma_f32 v[206:207], v[88:89], v[230:231], v[232:233] op_sel_hi:[0,1,1] neg_lo:[1,0,0] neg_hi:[1,0,0]
	v_pk_fma_f32 v[208:209], v[88:89], v[230:231], v[234:235] op_sel:[1,0,0] neg_lo:[1,0,0] neg_hi:[1,0,0]
	v_pk_fma_f32 v[210:211], v[90:91], v[230:231], v[236:237] op_sel_hi:[0,1,1] neg_lo:[1,0,0] neg_hi:[1,0,0]
	v_pk_fma_f32 v[212:213], v[90:91], v[230:231], v[238:239] op_sel:[1,0,0] neg_lo:[1,0,0] neg_hi:[1,0,0]
	s_waitcnt lgkmcnt(5)
	ds_read_b128 v[56:59], v242 offset:49856
	v_pk_mul_f32 v[226:227], v[206:207], v[106:107] op_sel_hi:[1,0]
	v_pk_mul_f32 v[228:229], v[206:207], v[222:223] op_sel_hi:[1,0]
	v_pk_fma_f32 v[226:227], v[208:209], v[106:107], v[226:227] op_sel:[0,1,0]
	v_pk_fma_f32 v[228:229], v[208:209], v[222:223], v[228:229] op_sel:[0,1,0]
	v_pk_fma_f32 v[226:227], v[210:211], v[108:109], v[226:227] op_sel_hi:[1,0,1]
	v_pk_fma_f32 v[228:229], v[210:211], v[224:225], v[228:229] op_sel_hi:[1,0,1]
	v_pk_fma_f32 v[226:227], v[212:213], v[108:109], v[226:227] op_sel:[0,1,0]
	v_pk_fma_f32 v[228:229], v[212:213], v[224:225], v[228:229] op_sel:[0,1,0]
	v_pk_fma_f32 v[232:233], v[60:61], v[114:115], v[206:207] op_sel_hi:[1,0,1]
	v_add_f32_dpp v230, v227, v226 row_ror:8 row_mask:0xf bank_mask:0xf
	v_pk_fma_f32 v[234:235], v[60:61], v[114:115], v[208:209] op_sel:[0,1,0]
	v_pk_fma_f32 v[236:237], v[60:61], v[116:117], v[210:211] op_sel_hi:[1,0,1]
	v_add_f32_dpp v230, v230, v230 quad_perm:[1,0,3,2] row_mask:0xf bank_mask:0xf
	v_pk_fma_f32 v[238:239], v[60:61], v[116:117], v[212:213] op_sel:[0,1,0]
	ds_read_b128 v[222:225], v240 offset:41072
	v_add_f32_dpp v230, v230, v230 quad_perm:[2,3,0,1] row_mask:0xf bank_mask:0xf
	ds_read_b128 v[92:95], v240 offset:32640
	ds_read_b128 v[88:91], v240 offset:23936
	v_add_f32_dpp v230, v230, v230 row_half_mirror row_mask:0xf bank_mask:0xf
	ds_write_b64 v217, v[228:229] offset:2880
	ds_read_b128 v[84:87], v240 offset:15232
	v_mov_b32_dpp v231, v230 row_ror:8 row_mask:0xf bank_mask:0xf
	v_pk_fma_f32 v[206:207], v[110:111], v[230:231], v[232:233] op_sel_hi:[0,1,1] neg_lo:[1,0,0] neg_hi:[1,0,0]
	v_pk_fma_f32 v[208:209], v[110:111], v[230:231], v[234:235] op_sel:[1,0,0] neg_lo:[1,0,0] neg_hi:[1,0,0]
	v_pk_fma_f32 v[210:211], v[112:113], v[230:231], v[236:237] op_sel_hi:[0,1,1] neg_lo:[1,0,0] neg_hi:[1,0,0]
	v_pk_fma_f32 v[212:213], v[112:113], v[230:231], v[238:239] op_sel:[1,0,0] neg_lo:[1,0,0] neg_hi:[1,0,0]
	s_waitcnt lgkmcnt(6)
; template <int CTRL> __device__ __forceinline__ float dppf(float x) { return __builtin_bit_cast(float, __builtin_amdgcn_update_dpp(0, __builtin_bit_cast(int, x), CTRL, 0xF, 0xF, false)); }
; __device__ __forceinline__ void phase_rwkv_scan(const Fr& F, int jr) {
;     ...
;                 for (int pg = 0; pg < 64; pg += 16) {
; #pragma unroll
;                     for (int pi = 0; pi < 16; ++pi) {
;                         const int p = pg + pi, pn = p < 63 ? p + 1 : 63;
;                         const f32x4 w4n = PW[pn * 16], k4n = PW[1024 + pn * 16], b4n = PW[2048 + pn * 16], d4n = PW[3072 + pn * 16], r4n = PR[pn * 16];
;                         const float vvn = PV[pn * 32];
;                         f32x2 t = S01 * k4.xy; t = S23 * k4.zw + t; float sa = t.x + t.y;
;                         sa += dppf<0x128>(sa);
;                         const f32x2 dv01 = d4.xy * vv, dv23 = d4.zw * vv;
;                         sa += dppf<0x124>(sa);
;                         const f32x2 e01 = S01 * w4.xy + dv01;
;                         sa += dppf<0x122>(sa);
;                         const f32x2 e23 = S23 * w4.zw + dv23;
;                         sa += dppf<0x121>(sa);
;                         S01 = e01 - b4.xy * sa; S23 = e23 - b4.zw * sa;
;                         f32x2 u = S01 * r4.xy; u = S23 * r4.zw + u;
;                         PY[pi * 64] = u.x + u.y;
;                         w4 = w4n; k4 = k4n; b4 = b4n; d4 = d4n; r4 = r4n; vv = vvn;
;                     }
	v_pk_mul_f32 v[226:227], v[206:207], v[4:5] op_sel_hi:[1,0]
	v_pk_mul_f32 v[228:229], v[206:207], v[96:97] op_sel_hi:[1,0]
	v_pk_fma_f32 v[226:227], v[208:209], v[4:5], v[226:227] op_sel:[0,1,0]
	v_pk_fma_f32 v[228:229], v[208:209], v[96:97], v[228:229] op_sel:[0,1,0]
	v_pk_fma_f32 v[226:227], v[210:211], v[6:7], v[226:227] op_sel_hi:[1,0,1]
	v_pk_fma_f32 v[228:229], v[210:211], v[98:99], v[228:229] op_sel_hi:[1,0,1]
	v_pk_fma_f32 v[226:227], v[212:213], v[6:7], v[226:227] op_sel:[0,1,0]
	v_pk_fma_f32 v[228:229], v[212:213], v[98:99], v[228:229] op_sel:[0,1,0]
	v_pk_fma_f32 v[232:233], v[62:63], v[12:13], v[206:207] op_sel_hi:[1,0,1]
	v_add_f32_dpp v230, v227, v226 row_ror:8 row_mask:0xf bank_mask:0xf
	v_pk_fma_f32 v[234:235], v[62:63], v[12:13], v[208:209] op_sel:[0,1,0]
	v_pk_fma_f32 v[236:237], v[62:63], v[14:15], v[210:211] op_sel_hi:[1,0,1]
	v_add_f32_dpp v230, v230, v230 quad_perm:[1,0,3,2] row_mask:0xf bank_mask:0xf
	v_pk_fma_f32 v[238:239], v[62:63], v[14:15], v[212:213] op_sel:[0,1,0]
	ds_read_b128 v[96:99], v240 offset:41344
	v_add_f32_dpp v230, v230, v230 quad_perm:[2,3,0,1] row_mask:0xf bank_mask:0xf
	ds_read_b128 v[114:117], v240 offset:32912
	ds_read_b128 v[110:113], v240 offset:24208
	v_add_f32_dpp v230, v230, v230 row_half_mirror row_mask:0xf bank_mask:0xf
	ds_write_b64 v217, v[228:229] offset:3456
	ds_read_b128 v[106:109], v240 offset:15504
	v_mov_b32_dpp v231, v230 row_ror:8 row_mask:0xf bank_mask:0xf
	v_pk_fma_f32 v[206:207], v[8:9], v[230:231], v[232:233] op_sel_hi:[0,1,1] neg_lo:[1,0,0] neg_hi:[1,0,0]
	v_pk_fma_f32 v[208:209], v[8:9], v[230:231], v[234:235] op_sel:[1,0,0] neg_lo:[1,0,0] neg_hi:[1,0,0]
	v_pk_fma_f32 v[210:211], v[10:11], v[230:231], v[236:237] op_sel_hi:[0,1,1] neg_lo:[1,0,0] neg_hi:[1,0,0]
	v_pk_fma_f32 v[212:213], v[10:11], v[230:231], v[238:239] op_sel:[1,0,0] neg_lo:[1,0,0] neg_hi:[1,0,0]
	s_waitcnt lgkmcnt(5)
	ds_read_b128 v[60:63], v242 offset:50384
	v_pk_mul_f32 v[226:227], v[206:207], v[84:85] op_sel_hi:[1,0]
	v_pk_mul_f32 v[228:229], v[206:207], v[222:223] op_sel_hi:[1,0]
	v_pk_fma_f32 v[226:227], v[208:209], v[84:85], v[226:227] op_sel:[0,1,0]
	v_pk_fma_f32 v[228:229], v[208:209], v[222:223], v[228:229] op_sel:[0,1,0]
	v_pk_fma_f32 v[226:227], v[210:211], v[86:87], v[226:227] op_sel_hi:[1,0,1]
	v_pk_fma_f32 v[228:229], v[210:211], v[224:225], v[228:229] op_sel_hi:[1,0,1]
	v_pk_fma_f32 v[226:227], v[212:213], v[86:87], v[226:227] op_sel:[0,1,0]
	v_pk_fma_f32 v[228:229], v[212:213], v[224:225], v[228:229] op_sel:[0,1,0]
	v_pk_fma_f32 v[232:233], v[56:57], v[92:93], v[206:207] op_sel_hi:[1,0,1]
	v_add_f32_dpp v230, v227, v226 row_ror:8 row_mask:0xf bank_mask:0xf
	v_pk_fma_f32 v[234:235], v[56:57], v[92:93], v[208:209] op_sel:[0,1,0]
	v_pk_fma_f32 v[236:237], v[56:57], v[94:95], v[210:211] op_sel_hi:[1,0,1]
	v_add_f32_dpp v230, v230, v230 quad_perm:[1,0,3,2] row_mask:0xf bank_mask:0xf
	v_pk_fma_f32 v[238:239], v[56:57], v[94:95], v[212:213] op_sel:[0,1,0]
	ds_read_b128 v[222:225], v240 offset:41616
	v_add_f32_dpp v230, v230, v230 quad_perm:[2,3,0,1] row_mask:0xf bank_mask:0xf
	ds_read_b128 v[12:15], v240 offset:33184
	ds_read_b128 v[8:11], v240 offset:24480
	v_add_f32_dpp v230, v230, v230 row_half_mirror row_mask:0xf bank_mask:0xf
	ds_write_b64 v217, v[228:229] offset:4032
	ds_read_b128 v[4:7], v240 offset:15776
	v_mov_b32_dpp v231, v230 row_ror:8 row_mask:0xf bank_mask:0xf
	v_pk_fma_f32 v[206:207], v[88:89], v[230:231], v[232:233] op_sel_hi:[0,1,1] neg_lo:[1,0,0] neg_hi:[1,0,0]
	v_pk_fma_f32 v[208:209], v[88:89], v[230:231], v[234:235] op_sel:[1,0,0] neg_lo:[1,0,0] neg_hi:[1,0,0]
	v_pk_fma_f32 v[210:211], v[90:91], v[230:231], v[236:237] op_sel_hi:[0,1,1] neg_lo:[1,0,0] neg_hi:[1,0,0]
	v_pk_fma_f32 v[212:213], v[90:91], v[230:231], v[238:239] op_sel:[1,0,0] neg_lo:[1,0,0] neg_hi:[1,0,0]
	s_waitcnt lgkmcnt(6)
	v_pk_mul_f32 v[226:227], v[206:207], v[106:107] op_sel_hi:[1,0]
	v_pk_mul_f32 v[228:229], v[206:207], v[96:97] op_sel_hi:[1,0]
	v_pk_fma_f32 v[226:227], v[208:209], v[106:107], v[226:227] op_sel:[0,1,0]
	v_pk_fma_f32 v[228:229], v[208:209], v[96:97], v[228:229] op_sel:[0,1,0]
	v_pk_fma_f32 v[226:227], v[210:211], v[108:109], v[226:227] op_sel_hi:[1,0,1]
	v_pk_fma_f32 v[228:229], v[210:211], v[98:99], v[228:229] op_sel_hi:[1,0,1]
	v_pk_fma_f32 v[226:227], v[212:213], v[108:109], v[226:227] op_sel:[0,1,0]
	v_pk_fma_f32 v[228:229], v[212:213], v[98:99], v[228:229] op_sel:[0,1,0]
	v_pk_fma_f32 v[232:233], v[58:59], v[114:115], v[206:207] op_sel_hi:[1,0,1]
	v_add_f32_dpp v230, v227, v226 row_ror:8 row_mask:0xf bank_mask:0xf
	v_pk_fma_f32 v[234:235], v[58:59], v[114:115], v[208:209] op_sel:[0,1,0]
	v_pk_fma_f32 v[236:237], v[58:59], v[116:117], v[210:211] op_sel_hi:[1,0,1]
	v_add_f32_dpp v230, v230, v230 quad_perm:[1,0,3,2] row_mask:0xf bank_mask:0xf
	v_pk_fma_f32 v[238:239], v[58:59], v[116:117], v[212:213] op_sel:[0,1,0]
	ds_read_b128 v[96:99], v240 offset:41888
	v_add_f32_dpp v230, v230, v230 quad_perm:[2,3,0,1] row_mask:0xf bank_mask:0xf
	ds_read_b128 v[92:95], v240 offset:33456
	ds_read_b128 v[88:91], v240 offset:24752
	v_add_f32_dpp v230, v230, v230 row_half_mirror row_mask:0xf bank_mask:0xf
	ds_write_b64 v217, v[228:229] offset:4608
	ds_read_b128 v[84:87], v240 offset:16048
	v_mov_b32_dpp v231, v230 row_ror:8 row_mask:0xf bank_mask:0xf
	v_pk_fma_f32 v[206:207], v[110:111], v[230:231], v[232:233] op_sel_hi:[0,1,1] neg_lo:[1,0,0] neg_hi:[1,0,0]
	v_pk_fma_f32 v[208:209], v[110:111], v[230:231], v[234:235] op_sel:[1,0,0] neg_lo:[1,0,0] neg_hi:[1,0,0]
	v_pk_fma_f32 v[210:211], v[112:113], v[230:231], v[236:237] op_sel_hi:[0,1,1] neg_lo:[1,0,0] neg_hi:[1,0,0]
	v_pk_fma_f32 v[212:213], v[112:113], v[230:231], v[238:239] op_sel:[1,0,0] neg_lo:[1,0,0] neg_hi:[1,0,0]
	s_waitcnt lgkmcnt(5)
; template <int CTRL> __device__ __forceinline__ float dppf(float x) { return __builtin_bit_cast(float, __builtin_amdgcn_update_dpp(0, __builtin_bit_cast(int, x), CTRL, 0xF, 0xF, false)); }
; __device__ __forceinline__ void phase_rwkv_scan(const Fr& F, int jr) {
;     ...
;                 for (int pg = 0; pg < 64; pg += 16) {
; #pragma unroll
;                     for (int pi = 0; pi < 16; ++pi) {
;                         const int p = pg + pi, pn = p < 63 ? p + 1 : 63;
;                         const f32x4 w4n = PW[pn * 16], k4n = PW[1024 + pn * 16], b4n = PW[2048 + pn * 16], d4n = PW[3072 + pn * 16], r4n = PR[pn * 16];
;                         const float vvn = PV[pn * 32];
;                         f32x2 t = S01 * k4.xy; t = S23 * k4.zw + t; float sa = t.x + t.y;
;                         sa += dppf<0x128>(sa);
;                         const f32x2 dv01 = d4.xy * vv, dv23 = d4.zw * vv;
;                         sa += dppf<0x124>(sa);
;                         const f32x2 e01 = S01 * w4.xy + dv01;
;                         sa += dppf<0x122>(sa);
;                         const f32x2 e23 = S23 * w4.zw + dv23;
;                         sa += dppf<0x121>(sa);
;                         S01 = e01 - b4.xy * sa; S23 = e23 - b4.zw * sa;
;                         f32x2 u = S01 * r4.xy; u = S23 * r4.zw + u;
;                         PY[pi * 64] = u.x + u.y;
;                         w4 = w4n; k4 = k4n; b4 = b4n; d4 = d4n; r4 = r4n; vv = vvn;
;                     }
	ds_read_b128 v[56:59], v242 offset:50912
	v_pk_mul_f32 v[226:227], v[206:207], v[4:5] op_sel_hi:[1,0]
	v_pk_mul_f32 v[228:229], v[206:207], v[222:223] op_sel_hi:[1,0]
	v_pk_fma_f32 v[226:227], v[208:209], v[4:5], v[226:227] op_sel:[0,1,0]
	v_pk_fma_f32 v[228:229], v[208:209], v[222:223], v[228:229] op_sel:[0,1,0]
	v_pk_fma_f32 v[226:227], v[210:211], v[6:7], v[226:227] op_sel_hi:[1,0,1]
	v_pk_fma_f32 v[228:229], v[210:211], v[224:225], v[228:229] op_sel_hi:[1,0,1]
	v_pk_fma_f32 v[226:227], v[212:213], v[6:7], v[226:227] op_sel:[0,1,0]
	v_pk_fma_f32 v[228:229], v[212:213], v[224:225], v[228:229] op_sel:[0,1,0]
	v_pk_fma_f32 v[232:233], v[60:61], v[12:13], v[206:207] op_sel_hi:[1,0,1]
	v_add_f32_dpp v230, v227, v226 row_ror:8 row_mask:0xf bank_mask:0xf
	v_pk_fma_f32 v[234:235], v[60:61], v[12:13], v[208:209] op_sel:[0,1,0]
	v_pk_fma_f32 v[236:237], v[60:61], v[14:15], v[210:211] op_sel_hi:[1,0,1]
	v_add_f32_dpp v230, v230, v230 quad_perm:[1,0,3,2] row_mask:0xf bank_mask:0xf
	v_pk_fma_f32 v[238:239], v[60:61], v[14:15], v[212:213] op_sel:[0,1,0]
	ds_read_b128 v[222:225], v240 offset:42160
	v_add_f32_dpp v230, v230, v230 quad_perm:[2,3,0,1] row_mask:0xf bank_mask:0xf
	ds_read_b128 v[114:117], v240 offset:33728
	ds_read_b128 v[110:113], v240 offset:25024
	v_add_f32_dpp v230, v230, v230 row_half_mirror row_mask:0xf bank_mask:0xf
	ds_write_b64 v217, v[228:229] offset:5184
	ds_read_b128 v[106:109], v240 offset:16320
	v_mov_b32_dpp v231, v230 row_ror:8 row_mask:0xf bank_mask:0xf
	v_pk_fma_f32 v[206:207], v[8:9], v[230:231], v[232:233] op_sel_hi:[0,1,1] neg_lo:[1,0,0] neg_hi:[1,0,0]
	v_pk_fma_f32 v[208:209], v[8:9], v[230:231], v[234:235] op_sel:[1,0,0] neg_lo:[1,0,0] neg_hi:[1,0,0]
	v_pk_fma_f32 v[210:211], v[10:11], v[230:231], v[236:237] op_sel_hi:[0,1,1] neg_lo:[1,0,0] neg_hi:[1,0,0]
	v_pk_fma_f32 v[212:213], v[10:11], v[230:231], v[238:239] op_sel:[1,0,0] neg_lo:[1,0,0] neg_hi:[1,0,0]
	s_waitcnt lgkmcnt(6)
	v_pk_mul_f32 v[226:227], v[206:207], v[84:85] op_sel_hi:[1,0]
	v_pk_mul_f32 v[228:229], v[206:207], v[96:97] op_sel_hi:[1,0]
	v_pk_fma_f32 v[226:227], v[208:209], v[84:85], v[226:227] op_sel:[0,1,0]
	v_pk_fma_f32 v[228:229], v[208:209], v[96:97], v[228:229] op_sel:[0,1,0]
	v_pk_fma_f32 v[226:227], v[210:211], v[86:87], v[226:227] op_sel_hi:[1,0,1]
	v_pk_fma_f32 v[228:229], v[210:211], v[98:99], v[228:229] op_sel_hi:[1,0,1]
	v_pk_fma_f32 v[226:227], v[212:213], v[86:87], v[226:227] op_sel:[0,1,0]
	v_pk_fma_f32 v[228:229], v[212:213], v[98:99], v[228:229] op_sel:[0,1,0]
	v_pk_fma_f32 v[232:233], v[62:63], v[92:93], v[206:207] op_sel_hi:[1,0,1]
	v_add_f32_dpp v230, v227, v226 row_ror:8 row_mask:0xf bank_mask:0xf
	v_pk_fma_f32 v[234:235], v[62:63], v[92:93], v[208:209] op_sel:[0,1,0]
	v_pk_fma_f32 v[236:237], v[62:63], v[94:95], v[210:211] op_sel_hi:[1,0,1]
	v_add_f32_dpp v230, v230, v230 quad_perm:[1,0,3,2] row_mask:0xf bank_mask:0xf
	v_pk_fma_f32 v[238:239], v[62:63], v[94:95], v[212:213] op_sel:[0,1,0]
	ds_read_b128 v[96:99], v240 offset:42432
	v_add_f32_dpp v230, v230, v230 quad_perm:[2,3,0,1] row_mask:0xf bank_mask:0xf
	ds_read_b128 v[12:15], v240 offset:34000
	ds_read_b128 v[8:11], v240 offset:25296
	v_add_f32_dpp v230, v230, v230 row_half_mirror row_mask:0xf bank_mask:0xf
	ds_write_b64 v217, v[228:229] offset:5760
	ds_read_b128 v[4:7], v240 offset:16592
	v_mov_b32_dpp v231, v230 row_ror:8 row_mask:0xf bank_mask:0xf
	v_pk_fma_f32 v[206:207], v[88:89], v[230:231], v[232:233] op_sel_hi:[0,1,1] neg_lo:[1,0,0] neg_hi:[1,0,0]
	v_pk_fma_f32 v[208:209], v[88:89], v[230:231], v[234:235] op_sel:[1,0,0] neg_lo:[1,0,0] neg_hi:[1,0,0]
	v_pk_fma_f32 v[210:211], v[90:91], v[230:231], v[236:237] op_sel_hi:[0,1,1] neg_lo:[1,0,0] neg_hi:[1,0,0]
	v_pk_fma_f32 v[212:213], v[90:91], v[230:231], v[238:239] op_sel:[1,0,0] neg_lo:[1,0,0] neg_hi:[1,0,0]
	s_waitcnt lgkmcnt(5)
	ds_read_b128 v[60:63], v242 offset:51440
	v_pk_mul_f32 v[226:227], v[206:207], v[106:107] op_sel_hi:[1,0]
	v_pk_mul_f32 v[228:229], v[206:207], v[222:223] op_sel_hi:[1,0]
	v_pk_fma_f32 v[226:227], v[208:209], v[106:107], v[226:227] op_sel:[0,1,0]
	v_pk_fma_f32 v[228:229], v[208:209], v[222:223], v[228:229] op_sel:[0,1,0]
	v_pk_fma_f32 v[226:227], v[210:211], v[108:109], v[226:227] op_sel_hi:[1,0,1]
	v_pk_fma_f32 v[228:229], v[210:211], v[224:225], v[228:229] op_sel_hi:[1,0,1]
	v_pk_fma_f32 v[226:227], v[212:213], v[108:109], v[226:227] op_sel:[0,1,0]
	v_pk_fma_f32 v[228:229], v[212:213], v[224:225], v[228:229] op_sel:[0,1,0]
	v_pk_fma_f32 v[232:233], v[56:57], v[114:115], v[206:207] op_sel_hi:[1,0,1]
	v_add_f32_dpp v230, v227, v226 row_ror:8 row_mask:0xf bank_mask:0xf
	v_pk_fma_f32 v[234:235], v[56:57], v[114:115], v[208:209] op_sel:[0,1,0]
	v_pk_fma_f32 v[236:237], v[56:57], v[116:117], v[210:211] op_sel_hi:[1,0,1]
	v_add_f32_dpp v230, v230, v230 quad_perm:[1,0,3,2] row_mask:0xf bank_mask:0xf
	v_pk_fma_f32 v[238:239], v[56:57], v[116:117], v[212:213] op_sel:[0,1,0]
	ds_read_b128 v[222:225], v240 offset:42704
	v_add_f32_dpp v230, v230, v230 quad_perm:[2,3,0,1] row_mask:0xf bank_mask:0xf
	ds_read_b128 v[92:95], v240 offset:34272
	ds_read_b128 v[88:91], v240 offset:25568
	v_add_f32_dpp v230, v230, v230 row_half_mirror row_mask:0xf bank_mask:0xf
	ds_write_b64 v217, v[228:229] offset:6336
	ds_read_b128 v[84:87], v240 offset:16864
	v_mov_b32_dpp v231, v230 row_ror:8 row_mask:0xf bank_mask:0xf
	v_pk_fma_f32 v[206:207], v[110:111], v[230:231], v[232:233] op_sel_hi:[0,1,1] neg_lo:[1,0,0] neg_hi:[1,0,0]
	v_pk_fma_f32 v[208:209], v[110:111], v[230:231], v[234:235] op_sel:[1,0,0] neg_lo:[1,0,0] neg_hi:[1,0,0]
	v_pk_fma_f32 v[210:211], v[112:113], v[230:231], v[236:237] op_sel_hi:[0,1,1] neg_lo:[1,0,0] neg_hi:[1,0,0]
	v_pk_fma_f32 v[212:213], v[112:113], v[230:231], v[238:239] op_sel:[1,0,0] neg_lo:[1,0,0] neg_hi:[1,0,0]
	s_waitcnt lgkmcnt(6)
; template <int CTRL> __device__ __forceinline__ float dppf(float x) { return __builtin_bit_cast(float, __builtin_amdgcn_update_dpp(0, __builtin_bit_cast(int, x), CTRL, 0xF, 0xF, false)); }
; __device__ __forceinline__ void phase_rwkv_scan(const Fr& F, int jr) {
;     ...
;                         const f32x4 w4n = PW[pn * 16], k4n = PW[1024 + pn * 16], b4n = PW[2048 + pn * 16], d4n = PW[3072 + pn * 16], r4n = PR[pn * 16];
;                         const float vvn = PV[pn * 32];
;                         f32x2 t = S01 * k4.xy; t = S23 * k4.zw + t; float sa = t.x + t.y;
;                         sa += dppf<0x128>(sa);
;                         const f32x2 dv01 = d4.xy * vv, dv23 = d4.zw * vv;
;                         sa += dppf<0x124>(sa);
;                         const f32x2 e01 = S01 * w4.xy + dv01;
;                         sa += dppf<0x122>(sa);
;                         const f32x2 e23 = S23 * w4.zw + dv23;
;                         sa += dppf<0x121>(sa);
;                         S01 = e01 - b4.xy * sa; S23 = e23 - b4.zw * sa;
;                         f32x2 u = S01 * r4.xy; u = S23 * r4.zw + u;
;                         PY[pi * 64] = u.x + u.y;
	v_pk_mul_f32 v[226:227], v[206:207], v[4:5] op_sel_hi:[1,0]
	v_pk_mul_f32 v[228:229], v[206:207], v[96:97] op_sel_hi:[1,0]
	v_pk_fma_f32 v[226:227], v[208:209], v[4:5], v[226:227] op_sel:[0,1,0]
	v_pk_fma_f32 v[228:229], v[208:209], v[96:97], v[228:229] op_sel:[0,1,0]
	v_pk_fma_f32 v[226:227], v[210:211], v[6:7], v[226:227] op_sel_hi:[1,0,1]
	v_pk_fma_f32 v[228:229], v[210:211], v[98:99], v[228:229] op_sel_hi:[1,0,1]
	v_pk_fma_f32 v[226:227], v[212:213], v[6:7], v[226:227] op_sel:[0,1,0]
	v_pk_fma_f32 v[228:229], v[212:213], v[98:99], v[228:229] op_sel:[0,1,0]
	v_pk_fma_f32 v[232:233], v[58:59], v[12:13], v[206:207] op_sel_hi:[1,0,1]
	v_add_f32_dpp v230, v227, v226 row_ror:8 row_mask:0xf bank_mask:0xf
	v_pk_fma_f32 v[234:235], v[58:59], v[12:13], v[208:209] op_sel:[0,1,0]
	v_pk_fma_f32 v[236:237], v[58:59], v[14:15], v[210:211] op_sel_hi:[1,0,1]
	v_add_f32_dpp v230, v230, v230 quad_perm:[1,0,3,2] row_mask:0xf bank_mask:0xf
	v_pk_fma_f32 v[238:239], v[58:59], v[14:15], v[212:213] op_sel:[0,1,0]
	ds_read_b128 v[96:99], v240 offset:42976
	v_add_f32_dpp v230, v230, v230 quad_perm:[2,3,0,1] row_mask:0xf bank_mask:0xf
	ds_read_b128 v[114:117], v240 offset:34544
	ds_read_b128 v[110:113], v240 offset:25840
	v_add_f32_dpp v230, v230, v230 row_half_mirror row_mask:0xf bank_mask:0xf
	ds_write_b64 v217, v[228:229] offset:6912
	ds_read_b128 v[106:109], v240 offset:17136
	ds_read_b128 v[102:105], v240 offset:8432
	v_mov_b32_dpp v231, v230 row_ror:8 row_mask:0xf bank_mask:0xf
	v_pk_fma_f32 v[206:207], v[8:9], v[230:231], v[232:233] op_sel_hi:[0,1,1] neg_lo:[1,0,0] neg_hi:[1,0,0]
	v_pk_fma_f32 v[208:209], v[8:9], v[230:231], v[234:235] op_sel:[1,0,0] neg_lo:[1,0,0] neg_hi:[1,0,0]
	v_pk_fma_f32 v[210:211], v[10:11], v[230:231], v[236:237] op_sel_hi:[0,1,1] neg_lo:[1,0,0] neg_hi:[1,0,0]
	v_pk_fma_f32 v[212:213], v[10:11], v[230:231], v[238:239] op_sel:[1,0,0] neg_lo:[1,0,0] neg_hi:[1,0,0]
	s_waitcnt lgkmcnt(6)
	v_pk_mul_f32 v[226:227], v[206:207], v[84:85] op_sel_hi:[1,0]
	v_pk_mul_f32 v[228:229], v[206:207], v[222:223] op_sel_hi:[1,0]
	v_pk_fma_f32 v[226:227], v[208:209], v[84:85], v[226:227] op_sel:[0,1,0]
	v_pk_fma_f32 v[228:229], v[208:209], v[222:223], v[228:229] op_sel:[0,1,0]
	v_pk_fma_f32 v[226:227], v[210:211], v[86:87], v[226:227] op_sel_hi:[1,0,1]
	v_pk_fma_f32 v[228:229], v[210:211], v[224:225], v[228:229] op_sel_hi:[1,0,1]
	v_pk_fma_f32 v[226:227], v[212:213], v[86:87], v[226:227] op_sel:[0,1,0]
	v_pk_fma_f32 v[228:229], v[212:213], v[224:225], v[228:229] op_sel:[0,1,0]
	v_pk_fma_f32 v[232:233], v[60:61], v[92:93], v[206:207] op_sel_hi:[1,0,1]
	v_add_f32_dpp v230, v227, v226 row_ror:8 row_mask:0xf bank_mask:0xf
	v_pk_fma_f32 v[234:235], v[60:61], v[92:93], v[208:209] op_sel:[0,1,0]
	v_pk_fma_f32 v[236:237], v[60:61], v[94:95], v[210:211] op_sel_hi:[1,0,1]
	v_add_f32_dpp v230, v230, v230 quad_perm:[1,0,3,2] row_mask:0xf bank_mask:0xf
	v_pk_fma_f32 v[238:239], v[60:61], v[94:95], v[212:213] op_sel:[0,1,0]
	ds_read_b128 v[222:225], v240 offset:43248
	v_add_f32_dpp v230, v230, v230 quad_perm:[2,3,0,1] row_mask:0xf bank_mask:0xf
	s_nop 1
	v_add_f32_dpp v230, v230, v230 row_half_mirror row_mask:0xf bank_mask:0xf
	ds_write_b64 v217, v[228:229] offset:7488
	s_nop 0
	v_mov_b32_dpp v231, v230 row_ror:8 row_mask:0xf bank_mask:0xf
	v_pk_fma_f32 v[206:207], v[88:89], v[230:231], v[232:233] op_sel_hi:[0,1,1] neg_lo:[1,0,0] neg_hi:[1,0,0]
	v_pk_fma_f32 v[208:209], v[88:89], v[230:231], v[234:235] op_sel:[1,0,0] neg_lo:[1,0,0] neg_hi:[1,0,0]
	v_pk_fma_f32 v[210:211], v[90:91], v[230:231], v[236:237] op_sel_hi:[0,1,1] neg_lo:[1,0,0] neg_hi:[1,0,0]
	v_pk_fma_f32 v[212:213], v[90:91], v[230:231], v[238:239] op_sel:[1,0,0] neg_lo:[1,0,0] neg_hi:[1,0,0]
	s_waitcnt lgkmcnt(3)
; __device__ __forceinline__ unsigned f2bf(float f) { unsigned u = __builtin_bit_cast(unsigned, f); return (u + 0x7fffu + ((u >> 16) & 1u)) >> 16; }
; template <int CTRL> __device__ __forceinline__ float dppf(float x) { return __builtin_bit_cast(float, __builtin_amdgcn_update_dpp(0, __builtin_bit_cast(int, x), CTRL, 0xF, 0xF, false)); }
; __device__ __forceinline__ void phase_rwkv_scan(const Fr& F, int jr) {
;     ...
;                         const f32x4 w4n = PW[pn * 16], k4n = PW[1024 + pn * 16], b4n = PW[2048 + pn * 16], d4n = PW[3072 + pn * 16], r4n = PR[pn * 16];
;                         const float vvn = PV[pn * 32];
;                         f32x2 t = S01 * k4.xy; t = S23 * k4.zw + t; float sa = t.x + t.y;
;                         sa += dppf<0x128>(sa);
;                         const f32x2 dv01 = d4.xy * vv, dv23 = d4.zw * vv;
;                         sa += dppf<0x124>(sa);
;                         const f32x2 e01 = S01 * w4.xy + dv01;
;                         sa += dppf<0x122>(sa);
;                         const f32x2 e23 = S23 * w4.zw + dv23;
;                         sa += dppf<0x121>(sa);
;                         S01 = e01 - b4.xy * sa; S23 = e23 - b4.zw * sa;
;                         f32x2 u = S01 * r4.xy; u = S23 * r4.zw + u;
;                         PY[pi * 64] = u.x + u.y;
;                         w4 = w4n; k4 = k4n; b4 = b4n; d4 = d4n; r4 = r4n; vv = vvn;
;                     }
;                     asm volatile("s_waitcnt lgkmcnt(0)" ::: "memory");
;                     {
;                         const int j = lane >> 2, q = lane & 3; const float* yp = Ypw + j * 64 + q * 16;
;                         const f32x4 a0 = *(const f32x4*)yp, a1 = *(const f32x4*)(yp + 4), a2 = *(const f32x4*)(yp + 8), a3 = *(const f32x4*)(yp + 12);
;                         const f32x4 ssum = (a0 + a1) + (a2 + a3); const float yv = (ssum.x + ssum.y) + (ssum.z + ssum.w);
;                         const size_t row = (size_t)b * TB + tokof(s, chunk * 64 + pg + j);
;                         Yb[row * D + h * 64 + 32 * half + 4 * wave + q] = (bf16)f2bf(yv);
;                     }
;                     asm volatile("s_waitcnt lgkmcnt(0)" ::: "memory");
	v_pk_mul_f32 v[226:227], v[206:207], v[106:107] op_sel_hi:[1,0]
	v_pk_mul_f32 v[228:229], v[206:207], v[96:97] op_sel_hi:[1,0]
	v_pk_fma_f32 v[226:227], v[208:209], v[106:107], v[226:227] op_sel:[0,1,0]
	v_pk_fma_f32 v[228:229], v[208:209], v[96:97], v[228:229] op_sel:[0,1,0]
	v_pk_fma_f32 v[226:227], v[210:211], v[108:109], v[226:227] op_sel_hi:[1,0,1]
	v_pk_fma_f32 v[228:229], v[210:211], v[98:99], v[228:229] op_sel_hi:[1,0,1]
	v_pk_fma_f32 v[226:227], v[212:213], v[108:109], v[226:227] op_sel:[0,1,0]
	v_pk_fma_f32 v[228:229], v[212:213], v[98:99], v[228:229] op_sel:[0,1,0]
	v_pk_fma_f32 v[232:233], v[62:63], v[114:115], v[206:207] op_sel_hi:[1,0,1]
	v_add_f32_dpp v230, v227, v226 row_ror:8 row_mask:0xf bank_mask:0xf
	v_pk_fma_f32 v[234:235], v[62:63], v[114:115], v[208:209] op_sel:[0,1,0]
	v_pk_fma_f32 v[236:237], v[62:63], v[116:117], v[210:211] op_sel_hi:[1,0,1]
	v_add_f32_dpp v230, v230, v230 quad_perm:[1,0,3,2] row_mask:0xf bank_mask:0xf
	v_pk_fma_f32 v[238:239], v[62:63], v[116:117], v[212:213] op_sel:[0,1,0]
	s_nop 0
	v_add_f32_dpp v230, v230, v230 quad_perm:[2,3,0,1] row_mask:0xf bank_mask:0xf
	s_nop 1
	v_add_f32_dpp v230, v230, v230 row_half_mirror row_mask:0xf bank_mask:0xf
	ds_write_b64 v217, v[228:229] offset:8064
	s_nop 0
	v_mov_b32_dpp v231, v230 row_ror:8 row_mask:0xf bank_mask:0xf
	v_pk_fma_f32 v[206:207], v[110:111], v[230:231], v[232:233] op_sel_hi:[0,1,1] neg_lo:[1,0,0] neg_hi:[1,0,0]
	v_pk_fma_f32 v[208:209], v[110:111], v[230:231], v[234:235] op_sel:[1,0,0] neg_lo:[1,0,0] neg_hi:[1,0,0]
	v_pk_fma_f32 v[210:211], v[112:113], v[230:231], v[236:237] op_sel_hi:[0,1,1] neg_lo:[1,0,0] neg_hi:[1,0,0]
	v_pk_fma_f32 v[212:213], v[112:113], v[230:231], v[238:239] op_sel:[1,0,0] neg_lo:[1,0,0] neg_hi:[1,0,0]
	s_waitcnt lgkmcnt(2)
	v_pk_mul_f32 v[228:229], v[206:207], v[222:223] op_sel_hi:[1,0]
	v_add_u32_e32 v243, s15, v219
	v_pk_fma_f32 v[228:229], v[208:209], v[222:223], v[228:229] op_sel:[0,1,0]
	v_lshl_add_u32 v243, v243, 11, v220
	v_pk_fma_f32 v[228:229], v[210:211], v[224:225], v[228:229] op_sel_hi:[1,0,1]
	v_pk_fma_f32 v[228:229], v[212:213], v[224:225], v[228:229] op_sel:[0,1,0]
	s_waitcnt lgkmcnt(1)
	ds_write_b64 v217, v[228:229] offset:8640
	v_pk_mul_f32 v[206:207], v[206:207], v[102:103] op_sel_hi:[1,0]
	v_pk_mul_f32 v[208:209], v[208:209], v[102:103] op_sel:[0,1]
	v_pk_mul_f32 v[210:211], v[210:211], v[104:105] op_sel_hi:[1,0]
	v_pk_mul_f32 v[212:213], v[212:213], v[104:105] op_sel:[0,1]
	ds_read_b128 v[24:27], v218 offset:0
	ds_read_b128 v[28:31], v218 offset:16
	ds_read_b128 v[32:35], v218 offset:32
	ds_read_b128 v[36:39], v218 offset:48
	ds_read_b128 v[40:43], v218 offset:64
	ds_read_b128 v[44:47], v218 offset:80
	ds_read_b128 v[48:51], v218 offset:96
	ds_read_b128 v[52:55], v218 offset:112
	s_waitcnt lgkmcnt(4)
	v_pk_add_f32 v[24:25], v[24:25], v[26:27]
	v_pk_add_f32 v[28:29], v[28:29], v[30:31]
	v_pk_add_f32 v[32:33], v[32:33], v[34:35]
	v_pk_add_f32 v[36:37], v[36:37], v[38:39]
	v_pk_add_f32 v[24:25], v[24:25], v[28:29]
	s_waitcnt lgkmcnt(0)
	v_pk_add_f32 v[40:41], v[40:41], v[42:43]
	v_pk_add_f32 v[44:45], v[44:45], v[46:47]
	v_pk_add_f32 v[32:33], v[32:33], v[36:37]
	v_pk_add_f32 v[48:49], v[48:49], v[50:51]
	v_pk_add_f32 v[52:53], v[52:53], v[54:55]
	v_pk_add_f32 v[40:41], v[40:41], v[44:45]
	v_pk_add_f32 v[24:25], v[24:25], v[32:33]
	v_pk_add_f32 v[48:49], v[48:49], v[52:53]
	s_add_i32 s15, s15, s19
	v_pk_add_f32 v[40:41], v[40:41], v[48:49]
	v_pk_add_f32 v[24:25], v[24:25], v[40:41] op_sel:[0,1] op_sel_hi:[1,0]
	v_cvt_pk_bf16_f32 v244, v24, v25
	global_store_dword v243, v244, s[20:21]
	s_waitcnt lgkmcnt(0)
	s_add_i32 s10, s10, 1
	s_xor_b32 s11, s11, 0xcc00
	s_cmp_eq_u32 s10, 8
	s_cselect_b32 s17, s18, 0
	s_add_i32 s15, s15, s17
	s_barrier
	s_cmp_lt_u32 s10, 136
	s_cbranch_scc1 .Lrw0_shc
	s_setprio 0
	s_branch .Lrw0_end

; __device__ __forceinline__ float sigm(float x) { return __builtin_amdgcn_rcpf(1.f + __expf(-x)); }
; template <int CTRL> __device__ __forceinline__ float dppf(float x) { return __builtin_bit_cast(float, __builtin_amdgcn_update_dpp(0, __builtin_bit_cast(int, x), CTRL, 0xF, 0xF, false)); }
; #define LDS_BAR() asm volatile("s_waitcnt lgkmcnt(0)\n\ts_barrier" ::: "memory")
; __device__ __forceinline__ void phase_rwkv_scan(const Fr& F, int jr) {
;     ...
;                     Wv[pp * 64 + hk] = __expf(-0.60653066f * sigm(w0v[hh] + cw[reg]));
;                     Av[pp * 64 + hk] = sigm(a0v[hh] + ca[reg]); }
;             }
;             LDS_BAR();
;             {
;                 const float kr[8] = {lo_bf(kw.x), hi_bf(kw.x), lo_bf(kw.y), hi_bf(kw.y), lo_bf(kw.z), hi_bf(kw.z), lo_bf(kw.w), hi_bf(kw.w)};
;                 const float rr[8] = {lo_bf(rw.x), hi_bf(rw.x), lo_bf(rw.y), hi_bf(rw.y), lo_bf(rw.z), hi_bf(rw.z), lo_bf(rw.w), hi_bf(rw.w)};
;                 float kq[8]; float ss = 0.f, bon = 0.f;
; #pragma unroll
;                 for (int i = 0; i < 8; ++i) { kq[i] = kr[i] * kkc[i]; ss += kq[i] * kq[i]; bon += rr[i] * kr[i] * rkc[i]; }
;                 ss += dppf<0xB1>(ss); ss += dppf<0x4E>(ss); ss += dppf<0x141>(ss); bon += dppf<0xB1>(bon); bon += dppf<0x4E>(bon); bon += dppf<0x141>(bon);
;                 if (s == 0 && half == 0 && j8 == 0) Bon[((size_t)b * TB + tokof(s, chunk * 64 + p2)) * 16 + h] = bon;
;                 const float inv = 1.f / fmaxf(sqrtf(ss), 1e-12f);
.Lrw0_hnl0:
	v_mov_b32_e32 v196, v232
	s_nop 1
	v_permlane16_swap_b32_e32 v232, v196
	s_nop 1
	v_add_f32_e32 v232, v232, v196
	v_mov_b32_e32 v196, v232
	s_nop 1
	v_permlane32_swap_b32_e32 v232, v196
	s_nop 1
	v_add_f32_e32 v232, v232, v196
	v_mul_f32_e32 v197, 0x4f800000, v232
	v_mov_b32_e32 v198, 0xf800000
	v_cmp_gt_f32_e32 vcc, v198, v232
	s_nop 1
	v_cndmask_b32_e32 v196, v232, v197, vcc
	v_sqrt_f32_e32 v197, v196
	s_nop 0
	v_add_u32_e32 v198, -1, v197
	v_fma_f32 v200, -v198, v197, v196
	v_add_u32_e32 v199, 1, v197
	v_cmp_ge_f32_e64 s[56:57], 0, v200
	s_nop 1
	v_cndmask_b32_e64 v198, v197, v198, s[56:57]
	v_fma_f32 v197, -v199, v197, v196
	v_cmp_lt_f32_e64 s[56:57], 0, v197
	s_nop 1
	v_cndmask_b32_e64 v197, v198, v199, s[56:57]
	v_mul_f32_e32 v198, 0x37800000, v197
	v_cndmask_b32_e32 v197, v197, v198, vcc
	v_mov_b32_e32 v198, 0x260
	v_cmp_class_f32_e32 vcc, v196, v198
	s_nop 1
	v_cndmask_b32_e32 v196, v197, v196, vcc
	v_max_f32_e32 v196, 0x2b8cbccc, v196
	v_div_scale_f32 v197, s[56:57], v196, v196, 1.0
	v_rcp_f32_e32 v198, v197
	s_nop 0
	v_fma_f32 v199, -v197, v198, 1.0
	v_fmac_f32_e32 v198, v199, v198
	v_div_scale_f32 v199, vcc, 1.0, v196, 1.0
	v_mul_f32_e32 v200, v199, v198
	v_fma_f32 v201, -v197, v200, v199
	v_fmac_f32_e32 v200, v201, v198
	v_fma_f32 v197, -v197, v200, v199
	s_nop 0
	v_div_fmas_f32 v197, v197, v198, v200
	v_div_fixup_f32 v232, v197, v196, 1.0
	v_pk_add_f32 v[136:137], v[32:33], v[136:137]
	v_pk_add_f32 v[138:139], v[34:35], v[138:139]
	v_pk_add_f32 v[144:145], v[40:41], v[144:145]
	v_pk_add_f32 v[146:147], v[42:43], v[146:147]
	v_pk_add_f32 v[140:141], v[36:37], v[140:141]
	v_pk_add_f32 v[142:143], v[38:39], v[142:143]
	v_pk_add_f32 v[148:149], v[44:45], v[148:149]
	v_pk_add_f32 v[150:151], v[46:47], v[150:151]
	v_pk_mul_f32 v[136:137], v[136:137], v[122:123]
	v_pk_mul_f32 v[138:139], v[138:139], v[122:123]
	v_pk_mul_f32 v[144:145], v[144:145], v[122:123]
	v_pk_mul_f32 v[146:147], v[146:147], v[122:123]
	v_pk_mul_f32 v[140:141], v[140:141], v[122:123]
	v_pk_mul_f32 v[142:143], v[142:143], v[122:123]
	v_pk_mul_f32 v[148:149], v[148:149], v[122:123]
	v_pk_mul_f32 v[150:151], v[150:151], v[122:123]
	v_exp_f32_e32 v136, v136
	v_exp_f32_e32 v137, v137
	v_exp_f32_e32 v138, v138
	v_exp_f32_e32 v139, v139
	v_exp_f32_e32 v144, v144
	v_exp_f32_e32 v145, v145
	v_exp_f32_e32 v146, v146
	v_exp_f32_e32 v147, v147
	v_exp_f32_e32 v140, v140
	v_exp_f32_e32 v141, v141
	v_exp_f32_e32 v142, v142
	v_exp_f32_e32 v143, v143
	v_exp_f32_e32 v148, v148
	v_exp_f32_e32 v149, v149
	v_exp_f32_e32 v150, v150
	v_exp_f32_e32 v151, v151
	v_pk_add_f32 v[136:137], v[136:137], 1.0 op_sel_hi:[1,0]
	v_pk_add_f32 v[138:139], v[138:139], 1.0 op_sel_hi:[1,0]
	v_pk_add_f32 v[144:145], v[144:145], 1.0 op_sel_hi:[1,0]
	v_pk_add_f32 v[146:147], v[146:147], 1.0 op_sel_hi:[1,0]
	v_pk_add_f32 v[140:141], v[140:141], 1.0 op_sel_hi:[1,0]
	v_pk_add_f32 v[142:143], v[142:143], 1.0 op_sel_hi:[1,0]
	v_pk_add_f32 v[148:149], v[148:149], 1.0 op_sel_hi:[1,0]
	v_pk_add_f32 v[150:151], v[150:151], 1.0 op_sel_hi:[1,0]
	v_rcp_f32_e32 v136, v136
	v_rcp_f32_e32 v137, v137
	v_rcp_f32_e32 v138, v138
	v_rcp_f32_e32 v139, v139
	v_rcp_f32_e32 v144, v144
	v_rcp_f32_e32 v145, v145
	v_rcp_f32_e32 v146, v146
	v_rcp_f32_e32 v147, v147
	v_rcp_f32_e32 v140, v140
	v_rcp_f32_e32 v141, v141
	v_rcp_f32_e32 v142, v142
	v_rcp_f32_e32 v143, v143
	v_rcp_f32_e32 v148, v148
	v_rcp_f32_e32 v149, v149
	v_rcp_f32_e32 v150, v150
	v_rcp_f32_e32 v151, v151
	v_pk_mul_f32 v[136:137], v[136:137], v[124:125]
	v_pk_mul_f32 v[138:139], v[138:139], v[124:125]
	v_pk_mul_f32 v[140:141], v[140:141], v[124:125]
	v_pk_mul_f32 v[142:143], v[142:143], v[124:125]
	v_pk_mul_f32 v[236:237], v[136:137], v[126:127]
	v_pk_mul_f32 v[238:239], v[138:139], v[126:127]
	v_pk_mul_f32 v[240:241], v[140:141], v[126:127]
	v_pk_mul_f32 v[242:243], v[142:143], v[126:127]
	v_pk_mul_f32 v[136:137], v[136:137], v[126:127]
	v_pk_mul_f32 v[138:139], v[138:139], v[126:127]
	v_pk_mul_f32 v[140:141], v[140:141], v[126:127]
	v_pk_mul_f32 v[142:143], v[142:143], v[126:127]
	v_add_f32_dpp v136, v136, v136 row_shr:1 row_mask:0xf bank_mask:0xf
	v_add_f32_dpp v137, v137, v137 row_shr:1 row_mask:0xf bank_mask:0xf
	v_add_f32_dpp v138, v138, v138 row_shr:1 row_mask:0xf bank_mask:0xf
	v_add_f32_dpp v139, v139, v139 row_shr:1 row_mask:0xf bank_mask:0xf
	v_add_f32_dpp v140, v140, v140 row_shr:1 row_mask:0xf bank_mask:0xf
	v_add_f32_dpp v141, v141, v141 row_shr:1 row_mask:0xf bank_mask:0xf
	v_add_f32_dpp v142, v142, v142 row_shr:1 row_mask:0xf bank_mask:0xf
	v_add_f32_dpp v143, v143, v143 row_shr:1 row_mask:0xf bank_mask:0xf
	v_add_f32_dpp v136, v136, v136 row_shr:2 row_mask:0xf bank_mask:0xf
	v_add_f32_dpp v137, v137, v137 row_shr:2 row_mask:0xf bank_mask:0xf
	v_add_f32_dpp v138, v138, v138 row_shr:2 row_mask:0xf bank_mask:0xf
	v_add_f32_dpp v139, v139, v139 row_shr:2 row_mask:0xf bank_mask:0xf
	v_add_f32_dpp v140, v140, v140 row_shr:2 row_mask:0xf bank_mask:0xf
	v_add_f32_dpp v141, v141, v141 row_shr:2 row_mask:0xf bank_mask:0xf
	v_add_f32_dpp v142, v142, v142 row_shr:2 row_mask:0xf bank_mask:0xf
	v_add_f32_dpp v143, v143, v143 row_shr:2 row_mask:0xf bank_mask:0xf
; template <int CTRL> __device__ __forceinline__ float dppf(float x) { return __builtin_bit_cast(float, __builtin_amdgcn_update_dpp(0, __builtin_bit_cast(int, x), CTRL, 0xF, 0xF, false)); }
; __device__ __forceinline__ void phase_rwkv_scan(const Fr& F, int jr) {
;     ...
;                 ss += dppf<0xB1>(ss); ss += dppf<0x4E>(ss); ss += dppf<0x141>(ss); bon += dppf<0xB1>(bon); bon += dppf<0x4E>(bon); bon += dppf<0x141>(bon);
;                 if (s == 0 && half == 0 && j8 == 0) Bon[((size_t)b * TB + tokof(s, chunk * 64 + p2)) * 16 + h] = bon;
;                 const float inv = 1.f / fmaxf(sqrtf(ss), 1e-12f);
;                 const f32x4 av0 = *(const f32x4*)(Av + p2 * 64 + hk0), av1 = *(const f32x4*)(Av + p2 * 64 + hk0 + 4);
;                 const float av[8] = {av0.x, av0.y, av0.z, av0.w, av1.x, av1.y, av1.z, av1.w};
;                 float o1[8], o2[8], o3[8];
; #pragma unroll
;                 for (int i = 0; i < 8; ++i) { const float kkv = kq[i] * inv; o1[i] = kkv; o2[i] = kkv * av[i]; o3[i] = kr[i] * (1.f + (av[i] - 1.f) * kac[i]); }
;                 const int o = p2 * 64 + hk0;
;                 *(f32x4*)(KK + o) = (f32x4){o1[0], o1[1], o1[2], o1[3]}; *(f32x4*)(KK + o + 4) = (f32x4){o1[4], o1[5], o1[6], o1[7]};
;                 *(f32x4*)(Bv + o) = (f32x4){o2[0], o2[1], o2[2], o2[3]}; *(f32x4*)(Bv + o + 4) = (f32x4){o2[4], o2[5], o2[6], o2[7]};
;                 *(f32x4*)(KD + o) = (f32x4){o3[0], o3[1], o3[2], o3[3]}; *(f32x4*)(KD + o + 4) = (f32x4){o3[4], o3[5], o3[6], o3[7]};
;                 *(f32x4*)(Rr + o) = (f32x4){rr[0], rr[1], rr[2], rr[3]}; *(f32x4*)(Rr + o + 4) = (f32x4){rr[4], rr[5], rr[6], rr[7]};
;                 *(f32x4*)(Vv + p2 * 32 + 4 * j8) = (f32x4){lo_bf(vw.x), hi_bf(vw.x), lo_bf(vw.y), hi_bf(vw.y)};
	v_add_f32_dpp v136, v136, v136 row_shr:4 row_mask:0xf bank_mask:0xf
	v_add_f32_dpp v137, v137, v137 row_shr:4 row_mask:0xf bank_mask:0xf
	v_add_f32_dpp v138, v138, v138 row_shr:4 row_mask:0xf bank_mask:0xf
	v_add_f32_dpp v139, v139, v139 row_shr:4 row_mask:0xf bank_mask:0xf
	v_add_f32_dpp v140, v140, v140 row_shr:4 row_mask:0xf bank_mask:0xf
	v_add_f32_dpp v141, v141, v141 row_shr:4 row_mask:0xf bank_mask:0xf
	v_add_f32_dpp v142, v142, v142 row_shr:4 row_mask:0xf bank_mask:0xf
	v_add_f32_dpp v143, v143, v143 row_shr:4 row_mask:0xf bank_mask:0xf
	v_add_f32_dpp v136, v136, v136 row_shr:8 row_mask:0xf bank_mask:0xf
	v_add_f32_dpp v137, v137, v137 row_shr:8 row_mask:0xf bank_mask:0xf
	v_add_f32_dpp v138, v138, v138 row_shr:8 row_mask:0xf bank_mask:0xf
	v_add_f32_dpp v139, v139, v139 row_shr:8 row_mask:0xf bank_mask:0xf
	v_add_f32_dpp v140, v140, v140 row_shr:8 row_mask:0xf bank_mask:0xf
	v_add_f32_dpp v141, v141, v141 row_shr:8 row_mask:0xf bank_mask:0xf
	v_add_f32_dpp v142, v142, v142 row_shr:8 row_mask:0xf bank_mask:0xf
	v_add_f32_dpp v143, v143, v143 row_shr:8 row_mask:0xf bank_mask:0xf
	v_pk_add_f32 v[236:237], v[136:137], v[236:237] neg_lo:[0,1] neg_hi:[0,1]
	v_pk_add_f32 v[238:239], v[138:139], v[238:239] neg_lo:[0,1] neg_hi:[0,1]
	v_pk_add_f32 v[240:241], v[140:141], v[240:241] neg_lo:[0,1] neg_hi:[0,1]
	v_pk_add_f32 v[242:243], v[142:143], v[242:243] neg_lo:[0,1] neg_hi:[0,1]
	v_exp_f32_e64 v244, -v136
	v_exp_f32_e64 v245, -v137
	v_exp_f32_e64 v246, -v138
	v_exp_f32_e64 v247, -v139
	v_exp_f32_e64 v248, -v140
	v_exp_f32_e64 v249, -v141
	v_exp_f32_e64 v250, -v142
	v_exp_f32_e64 v251, -v143
	v_exp_f32_e32 v236, v236
	v_exp_f32_e32 v237, v237
	v_exp_f32_e32 v238, v238
	v_exp_f32_e32 v239, v239
	v_exp_f32_e32 v240, v240
	v_exp_f32_e32 v241, v241
	v_exp_f32_e32 v242, v242
	v_exp_f32_e32 v243, v243
	v_exp_f32_e32 v136, v136
	v_exp_f32_e32 v137, v137
	v_exp_f32_e32 v138, v138
	v_exp_f32_e32 v139, v139
	v_exp_f32_e32 v140, v140
	v_exp_f32_e32 v141, v141
	v_exp_f32_e32 v142, v142
	v_exp_f32_e32 v143, v143
	v_pk_mul_f32 v[204:205], v[176:177], v[232:233] op_sel_hi:[1,0]
	v_pk_mul_f32 v[206:207], v[178:179], v[232:233] op_sel_hi:[1,0]
	v_pk_add_f32 v[212:213], v[144:145], -1.0 op_sel_hi:[1,0]
	v_pk_add_f32 v[214:215], v[146:147], -1.0 op_sel_hi:[1,0]
	v_pk_mul_f32 v[208:209], v[204:205], v[144:145]
	v_pk_mul_f32 v[210:211], v[206:207], v[146:147]
	v_pk_fma_f32 v[212:213], v[64:65], v[212:213], 1.0 op_sel_hi:[1,1,0]
	v_pk_fma_f32 v[214:215], v[66:67], v[214:215], 1.0 op_sel_hi:[1,1,0]
	ds_write_b128 v224, v[136:139] offset:0
	v_pk_mul_f32 v[204:205], v[204:205], v[236:237]
	v_pk_mul_f32 v[206:207], v[206:207], v[238:239]
	v_pk_mul_f32 v[212:213], v[212:213], v[152:153]
	v_pk_mul_f32 v[214:215], v[214:215], v[154:155]
	ds_write_b128 v224, v[204:207] offset:8704
	v_pk_mul_f32 v[208:209], v[208:209], v[244:245]
	v_pk_mul_f32 v[210:211], v[210:211], v[246:247]
	v_pk_mul_f32 v[196:197], v[168:169], v[136:137]
	v_pk_mul_f32 v[198:199], v[170:171], v[138:139]
	ds_write_b128 v224, v[208:211] offset:17408
	v_pk_mul_f32 v[212:213], v[212:213], v[244:245]
	v_pk_mul_f32 v[214:215], v[214:215], v[246:247]
	ds_write_b128 v224, v[196:199] offset:34816
	ds_write_b128 v224, v[212:215] offset:26112
	v_pk_mul_f32 v[204:205], v[180:181], v[232:233] op_sel_hi:[1,0]
	v_pk_mul_f32 v[206:207], v[182:183], v[232:233] op_sel_hi:[1,0]
	v_pk_add_f32 v[212:213], v[148:149], -1.0 op_sel_hi:[1,0]
	v_pk_add_f32 v[214:215], v[150:151], -1.0 op_sel_hi:[1,0]
	v_pk_mul_f32 v[208:209], v[204:205], v[148:149]
	v_pk_mul_f32 v[210:211], v[206:207], v[150:151]
	v_pk_fma_f32 v[212:213], v[68:69], v[212:213], 1.0 op_sel_hi:[1,1,0]
	v_pk_fma_f32 v[214:215], v[70:71], v[214:215], 1.0 op_sel_hi:[1,1,0]
	ds_write_b128 v224, v[140:143] offset:64
	v_pk_mul_f32 v[204:205], v[204:205], v[240:241]
	v_pk_mul_f32 v[206:207], v[206:207], v[242:243]
	v_pk_mul_f32 v[212:213], v[212:213], v[156:157]
	v_pk_mul_f32 v[214:215], v[214:215], v[158:159]
	ds_write_b128 v224, v[204:207] offset:8768
	v_pk_mul_f32 v[208:209], v[208:209], v[248:249]
	v_pk_mul_f32 v[210:211], v[210:211], v[250:251]
	v_pk_mul_f32 v[196:197], v[172:173], v[140:141]
	v_pk_mul_f32 v[198:199], v[174:175], v[142:143]
	ds_write_b128 v224, v[208:211] offset:17472
	v_pk_mul_f32 v[212:213], v[212:213], v[248:249]
	v_pk_mul_f32 v[214:215], v[214:215], v[250:251]
	ds_write_b128 v224, v[196:199] offset:34880
	ds_write_b128 v224, v[212:215] offset:26176
	v_mov_b32_e32 v204, v193
	v_mov_b32_e32 v205, v192
	v_mov_b32_e32 v206, v195
	v_mov_b32_e32 v207, v194
	ds_write_b64 v225, v[192:193] offset:43520
	ds_write_b64 v225, v[204:205] offset:43536
	ds_write_b64 v225, v[194:195] offset:43552
	ds_write_b64 v225, v[206:207] offset:43568
	s_cmp_eq_u32 s32, 0
	s_cbranch_scc1 .Lrw0_hnb0
	v_mov_b32_e32 v196, v234
	s_nop 1
	v_permlane16_swap_b32_e32 v234, v196
	s_nop 1
	v_add_f32_e32 v234, v234, v196
	v_mov_b32_e32 v196, v234
	s_nop 1
	v_permlane32_swap_b32_e32 v234, v196
	s_nop 1
	v_add_f32_e32 v234, v234, v196
	v_cmp_gt_u32_e32 vcc, 16, v130
	s_and_saveexec_b64 s[56:57], vcc
	global_store_dword v202, v234, s[44:45]
	s_mov_b64 exec, s[56:57]
